# GLA lin_prep (kv and linear-attention items): the four broadcast LDS reads of each row issued together into own registers with counted waits
# baseline (speedup 1.0000x reference)
.Lsw5_done:
	s_add_i32 s6, s18, 0xfffffa00
	s_mul_i32 s7, s6, 0xcccd
	s_lshr_b32 s6, s6, 6
	s_lshr_b32 s40, s7, 25
	s_mul_i32 s7, s6, 0xcd
	s_bfe_u32 s7, s7, 0x5000b
	s_mul_i32 s7, s7, 10
	s_sub_i32 s6, s6, s7
	s_nop 0
	v_mov_b32_e32 v53, v154
	s_and_b32 s37, s6, 0xff
	s_and_b32 s41, s18, 63
	s_lshl_b32 s34, s40, 12
	v_readfirstlane_b32 s6, v53
	s_lshl_b32 s35, s41, 6
	s_ashr_i32 s36, s6, 2
	s_or_b32 s34, s34, s35
	s_and_b32 s35, s36, -16
	s_ashr_i32 s6, s35, 31
	s_add_u32 s72, s35, s34
	v_and_b32_e32 v60, 63, v53
	s_addc_u32 s6, s6, 0
	s_lshl_b32 s34, s37, 6
	v_or_b32_e32 v0, s34, v60
	s_mul_hi_i32 s38, s72, 0x280
	s_mul_i32 s39, s72, 0x280
	v_or_b32_e32 v2, s39, v0
	v_mov_b32_e32 v3, s38
	v_lshlrev_b64 v[2:3], 1, v[2:3]
	v_lshl_add_u64 v[4:5], s[50:51], 0, v[2:3]
	v_add_co_u32_e32 v6, vcc, s88, v4
	v_lshl_add_u64 v[2:3], s[52:53], 0, v[2:3]
	s_nop 0
	v_addc_co_u32_e32 v7, vcc, 0, v5, vcc
	v_add_co_u32_e32 v8, vcc, s88, v2
	s_movk_i32 s42, 0x2000
	s_nop 0
	v_addc_co_u32_e32 v9, vcc, 0, v3, vcc
	s_add_u32 s39, s39, 0x1400
	s_barrier
	global_load_ushort v93, v[4:5], off
	global_load_ushort v91, v[4:5], off offset:1280
	global_load_ushort v89, v[4:5], off offset:2560
	global_load_ushort v87, v[4:5], off offset:3840
	global_load_ushort v94, v[2:3], off
	global_load_ushort v92, v[2:3], off offset:1280
	global_load_ushort v90, v[2:3], off offset:2560
	global_load_ushort v88, v[2:3], off offset:3840
	global_load_ushort v85, v[6:7], off offset:1024
	global_load_ushort v83, v[6:7], off offset:2304
	global_load_ushort v80, v[6:7], off offset:3584
	global_load_ushort v86, v[8:9], off offset:1024
	global_load_ushort v84, v[8:9], off offset:2304
	global_load_ushort v79, v[8:9], off offset:3584
	v_add_co_u32_e32 v6, vcc, s42, v4
	s_addc_u32 s38, s38, 0
	s_nop 0
	v_addc_co_u32_e32 v7, vcc, 0, v5, vcc
	v_or_b32_e32 v10, s39, v0
	v_mov_b32_e32 v11, s38
	v_add_co_u32_e32 v8, vcc, s42, v2
	v_lshlrev_b64 v[10:11], 1, v[10:11]
	s_nop 0
	v_addc_co_u32_e32 v9, vcc, 0, v3, vcc
	v_lshl_add_u64 v[12:13], s[50:51], 0, v[10:11]
	v_lshl_add_u64 v[10:11], s[52:53], 0, v[10:11]
	s_movk_i32 s38, 0x3000
	global_load_ushort v78, v[12:13], off
	global_load_ushort v77, v[10:11], off
	global_load_ushort v82, v[6:7], off offset:768
	global_load_ushort v76, v[6:7], off offset:3328
	global_load_ushort v81, v[8:9], off offset:768
	global_load_ushort v75, v[8:9], off offset:3328
	v_add_co_u32_e32 v6, vcc, s38, v4
	s_mul_i32 s7, s40, 10
	s_nop 0
	v_addc_co_u32_e32 v7, vcc, 0, v5, vcc
	v_add_co_u32_e32 v8, vcc, s38, v2
	s_add_i32 s7, s7, s37
	s_nop 0
	v_addc_co_u32_e32 v9, vcc, 0, v3, vcc
	v_add_co_u32_e32 v4, vcc, s47, v4
	v_ashrrev_i32_e32 v20, 3, v53
	s_nop 0
	v_addc_co_u32_e32 v5, vcc, 0, v5, vcc
	v_add_co_u32_e32 v2, vcc, s47, v2
	v_lshlrev_b32_e32 v0, 3, v53
	s_lshl_b32 s66, s7, 6
	s_lshl_b32 s7, s41, 7
	v_addc_co_u32_e32 v3, vcc, 0, v3, vcc
	v_and_b32_e32 v61, 56, v0
	v_ashrrev_i32_e32 v21, 31, v20
	s_add_u32 s38, s54, s7
	global_load_ushort v73, v[6:7], off offset:512
	global_load_ushort v71, v[6:7], off offset:1792
	global_load_ushort v70, v[6:7], off offset:3072
	global_load_ushort v74, v[8:9], off offset:512
	global_load_ushort v72, v[8:9], off offset:1792
	global_load_ushort v69, v[8:9], off offset:3072
	global_load_ushort v67, v[4:5], off offset:256
	global_load_ushort v64, v[4:5], off offset:1536
	global_load_ushort v63, v[4:5], off offset:2816
	global_load_ushort v68, v[2:3], off offset:256
	global_load_ushort v65, v[2:3], off offset:1536
	global_load_ushort v62, v[2:3], off offset:2816
	v_lshl_add_u64 v[2:3], v[20:21], 0, s[66:67]
	s_addc_u32 s39, s55, 0
	v_lshlrev_b32_e32 v0, 1, v61
	s_or_b32 s7, s66, s41
	v_lshl_add_u64 v[4:5], s[38:39], 0, v[0:1]
	s_lshl_b32 s7, s7, 13
	v_lshlrev_b64 v[2:3], 13, v[2:3]
	s_add_u32 s38, s24, s7
	v_lshl_add_u64 v[10:11], v[4:5], 0, v[2:3]
	s_mov_b32 s7, 0x40000
	s_addc_u32 s39, s25, 0
	global_load_dwordx4 v[2:5], v[10:11], off
	v_add_co_u32_e32 v10, vcc, s7, v10
	s_lshl_b32 s7, s37, 8
	v_lshl_add_u64 v[14:15], s[38:39], 0, v[0:1]
	s_add_u32 s38, s89, s7
	s_addc_u32 s39, s90, 0
	s_add_u32 s66, s38, 0xfffffa00
	s_addc_u32 s73, s39, -1
	s_add_u32 s7, s20, s7
	s_addc_u32 s74, s21, 0
	s_cmp_lt_u32 s37, 6
	s_cselect_b64 s[38:39], -1, 0
	v_lshlrev_b32_e32 v16, 6, v20
	v_bfe_u32 v66, v53, 4, 2
	s_and_b64 s[42:43], s[38:39], exec
	v_ashrrev_i32_e32 v17, 31, v16
	s_cselect_b32 s43, s74, s73
	s_cselect_b32 s42, s7, s66
	v_lshlrev_b32_e32 v59, 2, v66
	s_lshl_b32 s7, s37, 7
	v_and_b32_e32 v54, 15, v53
	v_lshl_add_u64 v[6:7], v[16:17], 1, v[14:15]
	v_add_u32_e32 v16, 0x800, v16
	v_or_b32_e32 v18, s72, v59
	s_add_u32 s72, s56, s7
	v_ashrrev_i32_e32 v17, 31, v16
	s_addc_u32 s73, s57, 0
	v_lshlrev_b32_e32 v0, 1, v54
	v_addc_co_u32_e32 v11, vcc, 0, v11, vcc
	v_lshl_add_u64 v[14:15], v[16:17], 1, v[14:15]
	v_lshl_add_u64 v[22:23], s[72:73], 0, v[0:1]
	v_lshlrev_b32_e32 v19, 2, v54
	s_movk_i32 s7, 0x500
	global_load_dwordx4 v[6:9], v[6:7], off nt
	v_mad_i64_i32 v[22:23], s[72:73], v18, s7, v[22:23]
	global_load_dwordx4 v[10:13], v[10:11], off
	v_mov_b32_e32 v99, v154
	global_load_dwordx4 v[14:17], v[14:15], off nt
	s_nop 0
	global_load_dword v40, v19, s[42:43]
	global_load_dword v39, v19, s[42:43] offset:64
	global_load_dword v38, v19, s[42:43] offset:128
	global_load_dword v21, v19, s[42:43] offset:192
	global_load_ushort v58, v[22:23], off
	global_load_ushort v52, v[22:23], off offset:1280
	global_load_ushort v55, v[22:23], off offset:32
	global_load_ushort v51, v[22:23], off offset:1312
	global_load_ushort v56, v[22:23], off offset:64
	global_load_ushort v50, v[22:23], off offset:1344
	global_load_ushort v49, v[22:23], off offset:1376
	global_load_ushort v57, v[22:23], off offset:96
	global_load_ushort v48, v[22:23], off offset:2560
	global_load_ushort v44, v[22:23], off offset:3840
	global_load_ushort v45, v[22:23], off offset:2592
	global_load_ushort v43, v[22:23], off offset:3872
	global_load_ushort v46, v[22:23], off offset:2624
	global_load_ushort v42, v[22:23], off offset:3904
	global_load_ushort v41, v[22:23], off offset:3936
	global_load_ushort v47, v[22:23], off offset:2656
	v_mov_b32_e32 v19, s6
	v_readfirstlane_b32 s43, v99
	s_ashr_i32 s42, s43, 6
	s_cmp_gt_u32 s37, 5
	s_mov_b64 s[6:7], -1
	s_cbranch_scc0 .LBB0_184
	s_lshl_b32 s6, s40, 18
	s_add_u32 s6, s26, s6
	s_addc_u32 s7, s27, 0
	s_lshl_b32 s40, s41, 12
	s_add_u32 s6, s6, s40
	v_lshlrev_b32_e32 v22, 2, v99
	s_addc_u32 s7, s7, 0
	v_ashrrev_i32_e32 v23, 31, v22
	v_and_b32_e32 v28, 63, v99
	v_lshl_add_u64 v[22:23], v[22:23], 2, s[6:7]
	s_add_i32 s6, s34, 0xfffffe80
	global_load_dwordx4 v[106:109], v[22:23], off
	v_or_b32_e32 v22, s6, v28
	v_mov_b32_e32 v23, v1
	v_lshlrev_b64 v[26:27], 2, v[22:23]
	v_lshl_add_u64 v[30:31], s[28:29], 0, v[26:27]
	s_movk_i32 s6, 0x2000
	v_add_co_u32_e32 v110, vcc, s6, v30
	s_movk_i32 s6, 0x3000
	s_nop 0
	v_addc_co_u32_e32 v111, vcc, 0, v31, vcc
	v_add_co_u32_e32 v34, vcc, s6, v30
	global_load_dword v22, v[110:111], off offset:2048
	global_load_dword v23, v[110:111], off offset:3072
	v_addc_co_u32_e32 v35, vcc, 0, v31, vcc
	global_load_dword v32, v[30:31], off
	global_load_dword v24, v[34:35], off
	v_lshl_add_u64 v[26:27], s[30:31], 0, v[26:27]
	global_load_dword v29, v[26:27], off
	global_load_dword v25, v[34:35], off offset:1024
	s_nop 0
	global_load_dword v26, v[34:35], off offset:2048
	global_load_dword v27, v[34:35], off offset:3072
	global_load_dword v95, v[30:31], off offset:1024
	global_load_dword v96, v[30:31], off offset:2048
	global_load_dword v97, v[30:31], off offset:3072
	global_load_dword v37, v[110:111], off offset:-4096
	v_add_co_u32_e32 v30, vcc, s88, v30
	s_lshl_b32 s6, s42, 10
	s_nop 0
	v_addc_co_u32_e32 v31, vcc, 0, v31, vcc
	global_load_dword v34, v[30:31], off offset:1024
	global_load_dword v35, v[30:31], off offset:2048
	global_load_dword v36, v[30:31], off offset:3072
	s_nop 0
	global_load_dword v30, v[110:111], off
	global_load_dword v31, v[110:111], off offset:1024
	v_lshlrev_b32_e32 v99, 4, v99
	v_mov_b32_e32 v33, s6
	s_and_b32 s6, s43, 0x3fffffc0
	s_cmp_gt_i32 s42, 0
	s_waitcnt vmcnt(17)
	ds_write_b128 v99, v[106:109] offset:55296
	s_waitcnt lgkmcnt(0)
	s_barrier
	ds_read_b128 v[106:109], v33 offset:55296
	ds_read_b128 v[110:113], v33 offset:55312
	ds_read_b128 v[114:117], v33 offset:55328
	ds_read_b128 v[118:121], v33 offset:55344
	ds_read_b128 v[122:125], v33 offset:55360
	ds_read_b128 v[126:129], v33 offset:55376
	ds_read_b128 v[130:133], v33 offset:55392
	ds_read_b128 v[134:137], v33 offset:55408
	s_waitcnt vmcnt(15) lgkmcnt(5)
	v_pk_mul_f32 v[116:117], v[22:23], v[116:117]
	s_waitcnt vmcnt(9) lgkmcnt(4)
	v_pk_mul_f32 v[120:121], v[26:27], v[120:121]
	v_fma_f32 v99, v32, v106, v29
	s_waitcnt vmcnt(8)
	v_fmac_f32_e32 v99, v95, v107
	s_waitcnt vmcnt(7)
	v_fmac_f32_e32 v99, v96, v108
	s_waitcnt vmcnt(6)
	v_fmac_f32_e32 v99, v97, v109
	s_waitcnt vmcnt(5)
	v_fmac_f32_e32 v99, v37, v110
	s_waitcnt lgkmcnt(3)
	v_fma_f32 v101, v32, v122, v29
	s_waitcnt vmcnt(4)
	v_fmac_f32_e32 v99, v34, v111
	v_fmac_f32_e32 v101, v95, v123
	s_waitcnt vmcnt(3)
	v_fmac_f32_e32 v99, v35, v112
	v_fmac_f32_e32 v101, v96, v124
	s_waitcnt vmcnt(2)
	v_fmac_f32_e32 v99, v36, v113
	v_fmac_f32_e32 v101, v97, v125
	s_waitcnt vmcnt(1)
	v_fmac_f32_e32 v99, v30, v114
	s_waitcnt lgkmcnt(2)
	v_fmac_f32_e32 v101, v37, v126
	s_waitcnt vmcnt(0)
	v_fmac_f32_e32 v99, v31, v115
	v_fmac_f32_e32 v101, v34, v127
	v_add_f32_e32 v99, v99, v116
	v_pk_mul_f32 v[118:119], v[24:25], v[118:119]
	v_fmac_f32_e32 v101, v35, v128
	v_add_f32_e32 v99, v99, v117
	v_fmac_f32_e32 v101, v36, v129
	v_add_f32_e32 v99, v99, v118
	s_waitcnt lgkmcnt(1)
	v_fmac_f32_e32 v101, v30, v130
	v_add_f32_e32 v99, v99, v119
	v_pk_mul_f32 v[132:133], v[22:23], v[132:133]
	v_fmac_f32_e32 v101, v31, v131
	v_add_f32_e32 v99, v99, v120
	v_add_f32_e32 v101, v101, v132
	v_add_f32_e32 v99, v99, v121
	s_waitcnt lgkmcnt(0)
	v_pk_mul_f32 v[134:135], v[24:25], v[134:135]
	v_add_f32_e32 v101, v101, v133
	v_mul_f32_e64 v103, |v99|, s46
	v_add_f32_e32 v101, v101, v134
	v_exp_f32_e32 v103, v103
	v_pk_mul_f32 v[136:137], v[26:27], v[136:137]
	v_add_f32_e32 v101, v101, v135
	v_add_f32_e32 v101, v101, v136
	v_add_f32_e32 v101, v101, v137
	v_mul_f32_e64 v105, |v101|, s46
	v_add_f32_e32 v103, 1.0, v103
	v_exp_f32_e32 v105, v105
	v_cmp_gt_f32_e32 vcc, s84, v103
	ds_read_b128 v[106:109], v33 offset:55424
	v_max_f32_e64 v99, -v99, 0
	v_cndmask_b32_e64 v110, 0, 32, vcc
	v_ldexp_f32 v103, v103, v110
	v_log_f32_e32 v103, v103
	v_add_f32_e32 v105, 1.0, v105
	v_cmp_gt_f32_e64 s[40:41], s84, v105
	v_cndmask_b32_e32 v110, 0, v161, vcc
	v_cmp_lt_f32_e64 vcc, |v103|, s45
	v_cndmask_b32_e64 v111, 0, 32, s[40:41]
	v_ldexp_f32 v105, v105, v111
	v_mul_f32_e32 v111, 0x3f317217, v103
	v_log_f32_e32 v105, v105
	v_fma_f32 v111, v103, s44, -v111
	v_fmac_f32_e32 v111, 0x3377d1cf, v103
	v_fmac_f32_e32 v111, 0x3f317217, v103
	v_cndmask_b32_e32 v103, v103, v111, vcc
	v_mul_f32_e32 v112, 0x3f317217, v105
	v_sub_f32_e32 v103, v103, v110
	v_add_f32_e32 v99, v99, v103
	v_fma_f32 v103, v105, s44, -v112
	ds_read_b128 v[110:113], v33 offset:55440
	ds_read_b128 v[142:145], v33 offset:55456
	ds_read_b128 v[146:149], v33 offset:55472
	s_waitcnt lgkmcnt(3)
	v_fma_f32 v114, v32, v106, v29
	v_fmac_f32_e32 v114, v95, v107
	v_fmac_f32_e32 v114, v96, v108
	v_fmac_f32_e32 v114, v97, v109
	s_waitcnt lgkmcnt(2)
	v_fmac_f32_e32 v114, v37, v110
	v_fmac_f32_e32 v114, v34, v111
	v_fmac_f32_e32 v114, v35, v112
	v_fmac_f32_e32 v114, v36, v113
	s_waitcnt lgkmcnt(1)
	v_fmac_f32_e32 v114, v30, v142
	v_fmac_f32_e32 v114, v31, v143
	v_pk_mul_f32 v[106:107], v[22:23], v[144:145]
	v_fmac_f32_e32 v103, 0x3377d1cf, v105
	v_add_f32_e32 v106, v114, v106
	v_add_f32_e32 v108, v106, v107
	s_waitcnt lgkmcnt(0)
	v_pk_mul_f32 v[106:107], v[24:25], v[146:147]
	v_fmac_f32_e32 v103, 0x3f317217, v105
	v_add_f32_e32 v106, v108, v106
	v_add_f32_e32 v108, v106, v107
	v_pk_mul_f32 v[106:107], v[26:27], v[148:149]
	v_cmp_lt_f32_e64 vcc, |v105|, s45
	v_add_f32_e32 v106, v108, v106
	v_add_f32_e32 v106, v106, v107
	v_mul_f32_e64 v107, |v106|, s46
	v_exp_f32_e32 v107, v107
	v_cndmask_b32_e32 v103, v105, v103, vcc
	v_cndmask_b32_e64 v105, 0, v161, s[40:41]
	v_max_f32_e64 v101, -v101, 0
	v_add_f32_e32 v107, 1.0, v107
	v_cmp_gt_f32_e32 vcc, s84, v107
	v_sub_f32_e32 v103, v103, v105
	v_add_f32_e32 v101, v101, v103
	v_cndmask_b32_e64 v108, 0, 32, vcc
	v_ldexp_f32 v107, v107, v108
	v_log_f32_e32 v114, v107
	v_max_f32_e64 v103, -v106, 0
	ds_read_b128 v[106:109], v33 offset:55488
	ds_read_b128 v[110:113], v33 offset:55504
	ds_read_b128 v[142:145], v33 offset:55520
	ds_read_b128 v[146:149], v33 offset:55536
	v_mul_f32_e32 v105, 0x3f317217, v114
	v_fma_f32 v105, v114, s44, -v105
	v_fmac_f32_e32 v105, 0x3377d1cf, v114
	s_waitcnt lgkmcnt(3)
	v_fma_f32 v115, v32, v106, v29
	v_fmac_f32_e32 v115, v95, v107
	v_fmac_f32_e32 v115, v96, v108
	v_fmac_f32_e32 v115, v97, v109
	s_waitcnt lgkmcnt(2)
	v_fmac_f32_e32 v115, v37, v110
	v_fmac_f32_e32 v115, v34, v111
	v_fmac_f32_e32 v115, v35, v112
	v_fmac_f32_e32 v115, v36, v113
	s_waitcnt lgkmcnt(1)
	v_fmac_f32_e32 v115, v30, v142
	v_fmac_f32_e32 v115, v31, v143
	v_pk_mul_f32 v[106:107], v[22:23], v[144:145]
	v_fmac_f32_e32 v105, 0x3f317217, v114
	v_add_f32_e32 v106, v115, v106
	v_add_f32_e32 v108, v106, v107
	s_waitcnt lgkmcnt(0)
	v_pk_mul_f32 v[106:107], v[24:25], v[146:147]
	v_cmp_lt_f32_e64 s[40:41], |v114|, s45
	v_add_f32_e32 v106, v108, v106
	v_add_f32_e32 v108, v106, v107
	v_pk_mul_f32 v[106:107], v[26:27], v[148:149]
	v_cndmask_b32_e64 v105, v114, v105, s[40:41]
	v_add_f32_e32 v106, v108, v106
	v_add_f32_e32 v106, v106, v107
	v_mul_f32_e64 v107, |v106|, s46
	v_exp_f32_e32 v107, v107
	v_cndmask_b32_e32 v108, 0, v161, vcc
	v_sub_f32_e32 v105, v105, v108
	v_add_f32_e32 v103, v103, v105
	v_add_f32_e32 v107, 1.0, v107
	v_cmp_gt_f32_e32 vcc, s84, v107
	v_max_f32_e64 v105, -v106, 0
	s_nop 0
	v_cndmask_b32_e64 v109, 0, 32, vcc
	v_ldexp_f32 v107, v107, v109
	v_log_f32_e32 v114, v107
	ds_read_b128 v[106:109], v33 offset:55552
	v_mul_f32_e32 v110, 0x3f317217, v114
	v_fma_f32 v115, v114, s44, -v110
	ds_read_b128 v[110:113], v33 offset:55568
	ds_read_b128 v[142:145], v33 offset:55584
	ds_read_b128 v[146:149], v33 offset:55600
	s_waitcnt lgkmcnt(3)
	v_fma_f32 v116, v32, v106, v29
	v_fmac_f32_e32 v116, v95, v107
	v_fmac_f32_e32 v116, v96, v108
	v_fmac_f32_e32 v116, v97, v109
	s_waitcnt lgkmcnt(2)
	v_fmac_f32_e32 v116, v37, v110
	v_fmac_f32_e32 v116, v34, v111
	v_fmac_f32_e32 v116, v35, v112
	v_fmac_f32_e32 v116, v36, v113
	s_waitcnt lgkmcnt(1)
	v_fmac_f32_e32 v116, v30, v142
	v_fmac_f32_e32 v116, v31, v143
	v_pk_mul_f32 v[106:107], v[22:23], v[144:145]
	v_fmac_f32_e32 v115, 0x3377d1cf, v114
	v_add_f32_e32 v106, v116, v106
	v_add_f32_e32 v108, v106, v107
	s_waitcnt lgkmcnt(0)
	v_pk_mul_f32 v[106:107], v[24:25], v[146:147]
	v_cndmask_b32_e32 v109, 0, v161, vcc
	v_add_f32_e32 v106, v108, v106
	v_add_f32_e32 v108, v106, v107
	v_pk_mul_f32 v[106:107], v[26:27], v[148:149]
	v_fmac_f32_e32 v115, 0x3f317217, v114
	v_add_f32_e32 v106, v108, v106
	v_add_f32_e32 v106, v106, v107
	v_mul_f32_e64 v107, |v106|, s46
	v_exp_f32_e32 v107, v107
	v_cmp_lt_f32_e64 s[40:41], |v114|, s45
	v_add_f32_e32 v107, 1.0, v107
	v_cmp_gt_f32_e32 vcc, s84, v107
	v_cndmask_b32_e64 v108, v114, v115, s[40:41]
	v_max_f32_e64 v115, -v106, 0
	v_cndmask_b32_e64 v110, 0, 32, vcc
	v_ldexp_f32 v107, v107, v110
	v_log_f32_e32 v114, v107
	v_sub_f32_e32 v107, v108, v109
	v_add_f32_e32 v105, v105, v107
	ds_read_b128 v[106:109], v33 offset:55616
	v_mul_f32_e32 v110, 0x3f317217, v114
	v_fma_f32 v116, v114, s44, -v110
	ds_read_b128 v[110:113], v33 offset:55632
	ds_read_b128 v[142:145], v33 offset:55648
	ds_read_b128 v[146:149], v33 offset:55664
	v_fmac_f32_e32 v116, 0x3377d1cf, v114
	s_waitcnt lgkmcnt(3)
	v_fma_f32 v117, v32, v106, v29
	v_fmac_f32_e32 v117, v95, v107
	v_fmac_f32_e32 v117, v96, v108
	v_fmac_f32_e32 v117, v97, v109
	s_waitcnt lgkmcnt(2)
	v_fmac_f32_e32 v117, v37, v110
	v_fmac_f32_e32 v117, v34, v111
	v_fmac_f32_e32 v117, v35, v112
	v_fmac_f32_e32 v117, v36, v113
	s_waitcnt lgkmcnt(1)
	v_fmac_f32_e32 v117, v30, v142
	v_fmac_f32_e32 v117, v31, v143
	v_pk_mul_f32 v[106:107], v[22:23], v[144:145]
	v_cndmask_b32_e32 v109, 0, v161, vcc
	v_add_f32_e32 v106, v117, v106
	v_add_f32_e32 v108, v106, v107
	s_waitcnt lgkmcnt(0)
	v_pk_mul_f32 v[106:107], v[24:25], v[146:147]
	v_fmac_f32_e32 v116, 0x3f317217, v114
	v_add_f32_e32 v106, v108, v106
	v_add_f32_e32 v108, v106, v107
	v_pk_mul_f32 v[106:107], v[26:27], v[148:149]
	v_cmp_lt_f32_e64 s[40:41], |v114|, s45
	v_add_f32_e32 v106, v108, v106
	v_add_f32_e32 v107, v106, v107
	v_mul_f32_e64 v106, |v107|, s46
	v_exp_f32_e32 v106, v106
	v_cndmask_b32_e64 v108, v114, v116, s[40:41]
	v_max_f32_e64 v107, -v107, 0
	v_add_f32_e32 v106, 1.0, v106
	v_cmp_gt_f32_e32 vcc, s84, v106
	s_nop 1
	v_cndmask_b32_e64 v110, 0, 32, vcc
	v_ldexp_f32 v106, v106, v110
	v_log_f32_e32 v116, v106
	v_sub_f32_e32 v106, v108, v109
	ds_read_b128 v[108:111], v33 offset:55680
	v_add_f32_e32 v106, v115, v106
	v_mul_f32_e32 v112, 0x3f317217, v116
	v_fma_f32 v117, v116, s44, -v112
	ds_read_b128 v[112:115], v33 offset:55696
	ds_read_b128 v[142:145], v33 offset:55712
	ds_read_b128 v[146:149], v33 offset:55728
	s_waitcnt lgkmcnt(3)
	v_fma_f32 v118, v32, v108, v29
	v_fmac_f32_e32 v118, v95, v109
	v_fmac_f32_e32 v118, v96, v110
	v_fmac_f32_e32 v118, v97, v111
	s_waitcnt lgkmcnt(2)
	v_fmac_f32_e32 v118, v37, v112
	v_fmac_f32_e32 v118, v34, v113
	v_fmac_f32_e32 v118, v35, v114
	v_fmac_f32_e32 v118, v36, v115
	s_waitcnt lgkmcnt(1)
	v_fmac_f32_e32 v118, v30, v142
	v_fmac_f32_e32 v118, v31, v143
	v_pk_mul_f32 v[108:109], v[22:23], v[144:145]
	v_fmac_f32_e32 v117, 0x3377d1cf, v116
	v_add_f32_e32 v108, v118, v108
	v_add_f32_e32 v110, v108, v109
	s_waitcnt lgkmcnt(0)
	v_pk_mul_f32 v[108:109], v[24:25], v[146:147]
	v_cndmask_b32_e32 v111, 0, v161, vcc
	v_add_f32_e32 v108, v110, v108
	v_add_f32_e32 v110, v108, v109
	v_pk_mul_f32 v[108:109], v[26:27], v[148:149]
	v_fmac_f32_e32 v117, 0x3f317217, v116
	v_add_f32_e32 v108, v110, v108
	v_add_f32_e32 v108, v108, v109
	v_mul_f32_e64 v109, |v108|, s46
	v_exp_f32_e32 v109, v109
	v_cmp_lt_f32_e64 s[40:41], |v116|, s45
	v_add_f32_e32 v109, 1.0, v109
	v_cmp_gt_f32_e32 vcc, s84, v109
	v_cndmask_b32_e64 v110, v116, v117, s[40:41]
	v_max_f32_e64 v117, -v108, 0
	v_cndmask_b32_e64 v112, 0, 32, vcc
	v_ldexp_f32 v109, v109, v112
	v_log_f32_e32 v116, v109
	v_sub_f32_e32 v109, v110, v111
	v_add_f32_e32 v107, v107, v109
	ds_read_b128 v[108:111], v33 offset:55744
	v_mul_f32_e32 v112, 0x3f317217, v116
	v_fma_f32 v118, v116, s44, -v112
	ds_read_b128 v[112:115], v33 offset:55760
	ds_read_b128 v[142:145], v33 offset:55776
	ds_read_b128 v[146:149], v33 offset:55792
	v_fmac_f32_e32 v118, 0x3377d1cf, v116
	s_waitcnt lgkmcnt(3)
	v_fma_f32 v119, v32, v108, v29
	v_fmac_f32_e32 v119, v95, v109
	v_fmac_f32_e32 v119, v96, v110
	v_fmac_f32_e32 v119, v97, v111
	s_waitcnt lgkmcnt(2)
	v_fmac_f32_e32 v119, v37, v112
	v_fmac_f32_e32 v119, v34, v113
	v_fmac_f32_e32 v119, v35, v114
	v_fmac_f32_e32 v119, v36, v115
	s_waitcnt lgkmcnt(1)
	v_fmac_f32_e32 v119, v30, v142
	v_fmac_f32_e32 v119, v31, v143
	v_pk_mul_f32 v[108:109], v[22:23], v[144:145]
	v_cndmask_b32_e32 v111, 0, v161, vcc
	v_add_f32_e32 v108, v119, v108
	v_add_f32_e32 v110, v108, v109
	s_waitcnt lgkmcnt(0)
	v_pk_mul_f32 v[108:109], v[24:25], v[146:147]
	v_fmac_f32_e32 v118, 0x3f317217, v116
	v_add_f32_e32 v108, v110, v108
	v_add_f32_e32 v110, v108, v109
	v_pk_mul_f32 v[108:109], v[26:27], v[148:149]
	v_cmp_lt_f32_e64 s[40:41], |v116|, s45
	v_add_f32_e32 v108, v110, v108
	v_add_f32_e32 v109, v108, v109
	v_mul_f32_e64 v108, |v109|, s46
	v_exp_f32_e32 v108, v108
	v_cndmask_b32_e64 v110, v116, v118, s[40:41]
	v_max_f32_e64 v109, -v109, 0
	v_add_f32_e32 v108, 1.0, v108
	v_cmp_gt_f32_e32 vcc, s84, v108
	s_nop 1
	v_cndmask_b32_e64 v112, 0, 32, vcc
	v_ldexp_f32 v108, v108, v112
	v_log_f32_e32 v118, v108
	v_sub_f32_e32 v108, v110, v111
	ds_read_b128 v[110:113], v33 offset:55808
	v_add_f32_e32 v108, v117, v108
	v_mul_f32_e32 v114, 0x3f317217, v118
	v_fma_f32 v119, v118, s44, -v114
	ds_read_b128 v[114:117], v33 offset:55824
	ds_read_b128 v[142:145], v33 offset:55840
	ds_read_b128 v[146:149], v33 offset:55856
	s_waitcnt lgkmcnt(3)
	v_fma_f32 v120, v32, v110, v29
	v_fmac_f32_e32 v120, v95, v111
	v_fmac_f32_e32 v120, v96, v112
	v_fmac_f32_e32 v120, v97, v113
	s_waitcnt lgkmcnt(2)
	v_fmac_f32_e32 v120, v37, v114
	v_fmac_f32_e32 v120, v34, v115
	v_fmac_f32_e32 v120, v35, v116
	v_fmac_f32_e32 v120, v36, v117
	s_waitcnt lgkmcnt(1)
	v_fmac_f32_e32 v120, v30, v142
	v_fmac_f32_e32 v120, v31, v143
	v_pk_mul_f32 v[110:111], v[22:23], v[144:145]
	v_fmac_f32_e32 v119, 0x3377d1cf, v118
	v_add_f32_e32 v110, v120, v110
	v_add_f32_e32 v112, v110, v111
	s_waitcnt lgkmcnt(0)
	v_pk_mul_f32 v[110:111], v[24:25], v[146:147]
	v_cndmask_b32_e32 v113, 0, v161, vcc
	v_add_f32_e32 v110, v112, v110
	v_add_f32_e32 v112, v110, v111
	v_pk_mul_f32 v[110:111], v[26:27], v[148:149]
	v_fmac_f32_e32 v119, 0x3f317217, v118
	v_add_f32_e32 v110, v112, v110
	v_add_f32_e32 v110, v110, v111
	v_mul_f32_e64 v111, |v110|, s46
	v_exp_f32_e32 v111, v111
	v_cmp_lt_f32_e64 s[40:41], |v118|, s45
	v_add_f32_e32 v111, 1.0, v111
	v_cmp_gt_f32_e32 vcc, s84, v111
	v_cndmask_b32_e64 v112, v118, v119, s[40:41]
	v_max_f32_e64 v119, -v110, 0
	v_cndmask_b32_e64 v114, 0, 32, vcc
	v_ldexp_f32 v111, v111, v114
	v_log_f32_e32 v118, v111
	v_sub_f32_e32 v111, v112, v113
	v_add_f32_e32 v109, v109, v111
	ds_read_b128 v[110:113], v33 offset:55872
	v_mul_f32_e32 v114, 0x3f317217, v118
	v_fma_f32 v120, v118, s44, -v114
	ds_read_b128 v[114:117], v33 offset:55888
	ds_read_b128 v[142:145], v33 offset:55904
	ds_read_b128 v[146:149], v33 offset:55920
	v_fmac_f32_e32 v120, 0x3377d1cf, v118
	s_waitcnt lgkmcnt(3)
	v_fma_f32 v121, v32, v110, v29
	v_fmac_f32_e32 v121, v95, v111
	v_fmac_f32_e32 v121, v96, v112
	v_fmac_f32_e32 v121, v97, v113
	s_waitcnt lgkmcnt(2)
	v_fmac_f32_e32 v121, v37, v114
	v_fmac_f32_e32 v121, v34, v115
	v_fmac_f32_e32 v121, v35, v116
	v_fmac_f32_e32 v121, v36, v117
	s_waitcnt lgkmcnt(1)
	v_fmac_f32_e32 v121, v30, v142
	v_fmac_f32_e32 v121, v31, v143
	v_pk_mul_f32 v[110:111], v[22:23], v[144:145]
	v_cndmask_b32_e32 v113, 0, v161, vcc
	v_add_f32_e32 v110, v121, v110
	v_add_f32_e32 v112, v110, v111
	s_waitcnt lgkmcnt(0)
	v_pk_mul_f32 v[110:111], v[24:25], v[146:147]
	v_fmac_f32_e32 v120, 0x3f317217, v118
	v_add_f32_e32 v110, v112, v110
	v_add_f32_e32 v112, v110, v111
	v_pk_mul_f32 v[110:111], v[26:27], v[148:149]
	v_cmp_lt_f32_e64 s[40:41], |v118|, s45
	v_add_f32_e32 v110, v112, v110
	v_add_f32_e32 v110, v110, v111
	v_mul_f32_e64 v111, |v110|, s46
	v_exp_f32_e32 v111, v111
	v_cndmask_b32_e64 v112, v118, v120, s[40:41]
	v_max_f32_e64 v120, -v110, 0
	v_add_f32_e32 v111, 1.0, v111
	v_cmp_gt_f32_e32 vcc, s84, v111
	s_nop 1
	v_cndmask_b32_e64 v114, 0, 32, vcc
	v_ldexp_f32 v111, v111, v114
	v_log_f32_e32 v118, v111
	v_sub_f32_e32 v111, v112, v113
	v_add_f32_e32 v119, v119, v111
	ds_read_b128 v[110:113], v33 offset:55936
	v_mul_f32_e32 v114, 0x3f317217, v118
	v_fma_f32 v121, v118, s44, -v114
	ds_read_b128 v[114:117], v33 offset:55952
	ds_read_b128 v[142:145], v33 offset:55968
	ds_read_b128 v[146:149], v33 offset:55984
	v_fmac_f32_e32 v121, 0x3377d1cf, v118
	s_waitcnt lgkmcnt(3)
	v_fma_f32 v122, v32, v110, v29
	v_fmac_f32_e32 v122, v95, v111
	v_fmac_f32_e32 v122, v96, v112
	v_fmac_f32_e32 v122, v97, v113
	s_waitcnt lgkmcnt(2)
	v_fmac_f32_e32 v122, v37, v114
	v_fmac_f32_e32 v122, v34, v115
	v_fmac_f32_e32 v122, v35, v116
	v_fmac_f32_e32 v122, v36, v117
	s_waitcnt lgkmcnt(1)
	v_fmac_f32_e32 v122, v30, v142
	v_fmac_f32_e32 v122, v31, v143
	v_pk_mul_f32 v[110:111], v[22:23], v[144:145]
	v_cndmask_b32_e32 v113, 0, v161, vcc
	v_add_f32_e32 v110, v122, v110
	v_add_f32_e32 v112, v110, v111
	s_waitcnt lgkmcnt(0)
	v_pk_mul_f32 v[110:111], v[24:25], v[146:147]
	v_fmac_f32_e32 v121, 0x3f317217, v118
	v_add_f32_e32 v110, v112, v110
	v_add_f32_e32 v112, v110, v111
	v_pk_mul_f32 v[110:111], v[26:27], v[148:149]
	v_cmp_lt_f32_e64 s[40:41], |v118|, s45
	v_add_f32_e32 v110, v112, v110
	v_add_f32_e32 v110, v110, v111
	v_mul_f32_e64 v111, |v110|, s46
	v_exp_f32_e32 v111, v111
	v_cndmask_b32_e64 v112, v118, v121, s[40:41]
	v_max_f32_e64 v121, -v110, 0
	v_add_f32_e32 v111, 1.0, v111
	v_cmp_gt_f32_e32 vcc, s84, v111
	s_nop 1
	v_cndmask_b32_e64 v114, 0, 32, vcc
	v_ldexp_f32 v111, v111, v114
	v_log_f32_e32 v118, v111
	v_sub_f32_e32 v111, v112, v113
	v_add_f32_e32 v120, v120, v111
	ds_read_b128 v[110:113], v33 offset:56000
	v_mul_f32_e32 v114, 0x3f317217, v118
	v_fma_f32 v122, v118, s44, -v114
	ds_read_b128 v[114:117], v33 offset:56016
	ds_read_b128 v[142:145], v33 offset:56032
	ds_read_b128 v[146:149], v33 offset:56048
	v_fmac_f32_e32 v122, 0x3377d1cf, v118
	s_waitcnt lgkmcnt(3)
	v_fma_f32 v123, v32, v110, v29
	v_fmac_f32_e32 v123, v95, v111
	v_fmac_f32_e32 v123, v96, v112
	v_fmac_f32_e32 v123, v97, v113
	s_waitcnt lgkmcnt(2)
	v_fmac_f32_e32 v123, v37, v114
	v_fmac_f32_e32 v123, v34, v115
	v_fmac_f32_e32 v123, v35, v116
	v_fmac_f32_e32 v123, v36, v117
	s_waitcnt lgkmcnt(1)
	v_fmac_f32_e32 v123, v30, v142
	v_fmac_f32_e32 v123, v31, v143
	v_pk_mul_f32 v[110:111], v[22:23], v[144:145]
	v_cndmask_b32_e32 v113, 0, v161, vcc
	v_add_f32_e32 v110, v123, v110
	v_add_f32_e32 v112, v110, v111
	s_waitcnt lgkmcnt(0)
	v_pk_mul_f32 v[110:111], v[24:25], v[146:147]
	v_fmac_f32_e32 v122, 0x3f317217, v118
	v_add_f32_e32 v110, v112, v110
	v_add_f32_e32 v112, v110, v111
	v_pk_mul_f32 v[110:111], v[26:27], v[148:149]
	v_cmp_lt_f32_e64 s[40:41], |v118|, s45
	v_add_f32_e32 v110, v112, v110
	v_add_f32_e32 v110, v110, v111
	v_mul_f32_e64 v111, |v110|, s46
	v_exp_f32_e32 v111, v111
	v_cndmask_b32_e64 v112, v118, v122, s[40:41]
	v_max_f32_e64 v122, -v110, 0
	v_add_f32_e32 v111, 1.0, v111
	v_cmp_gt_f32_e32 vcc, s84, v111
	s_nop 1
	v_cndmask_b32_e64 v114, 0, 32, vcc
	v_ldexp_f32 v111, v111, v114
	v_log_f32_e32 v118, v111
	v_sub_f32_e32 v111, v112, v113
	v_add_f32_e32 v121, v121, v111
	ds_read_b128 v[110:113], v33 offset:56064
	v_mul_f32_e32 v114, 0x3f317217, v118
	v_fma_f32 v123, v118, s44, -v114
	ds_read_b128 v[114:117], v33 offset:56080
	ds_read_b128 v[142:145], v33 offset:56096
	ds_read_b128 v[146:149], v33 offset:56112
	v_fmac_f32_e32 v123, 0x3377d1cf, v118
	s_waitcnt lgkmcnt(3)
	v_fma_f32 v124, v32, v110, v29
	v_fmac_f32_e32 v124, v95, v111
	v_fmac_f32_e32 v124, v96, v112
	v_fmac_f32_e32 v124, v97, v113
	s_waitcnt lgkmcnt(2)
	v_fmac_f32_e32 v124, v37, v114
	v_fmac_f32_e32 v124, v34, v115
	v_fmac_f32_e32 v124, v35, v116
	v_fmac_f32_e32 v124, v36, v117
	s_waitcnt lgkmcnt(1)
	v_fmac_f32_e32 v124, v30, v142
	v_fmac_f32_e32 v124, v31, v143
	v_pk_mul_f32 v[110:111], v[22:23], v[144:145]
	v_cndmask_b32_e32 v113, 0, v161, vcc
	v_add_f32_e32 v110, v124, v110
	v_add_f32_e32 v112, v110, v111
	s_waitcnt lgkmcnt(0)
	v_pk_mul_f32 v[110:111], v[24:25], v[146:147]
	v_fmac_f32_e32 v123, 0x3f317217, v118
	v_add_f32_e32 v110, v112, v110
	v_add_f32_e32 v112, v110, v111
	v_pk_mul_f32 v[110:111], v[26:27], v[148:149]
	v_cmp_lt_f32_e64 s[40:41], |v118|, s45
	v_add_f32_e32 v110, v112, v110
	v_add_f32_e32 v110, v110, v111
	v_mul_f32_e64 v111, |v110|, s46
	v_exp_f32_e32 v111, v111
	v_cndmask_b32_e64 v112, v118, v123, s[40:41]
	v_max_f32_e64 v123, -v110, 0
	v_add_f32_e32 v111, 1.0, v111
	v_cmp_gt_f32_e32 vcc, s84, v111
	s_nop 1
	v_cndmask_b32_e64 v114, 0, 32, vcc
	v_ldexp_f32 v111, v111, v114
	v_log_f32_e32 v118, v111
	v_sub_f32_e32 v111, v112, v113
	v_add_f32_e32 v122, v122, v111
	ds_read_b128 v[110:113], v33 offset:56128
	v_mul_f32_e32 v114, 0x3f317217, v118
	v_fma_f32 v124, v118, s44, -v114
	ds_read_b128 v[114:117], v33 offset:56144
	ds_read_b128 v[142:145], v33 offset:56160
	ds_read_b128 v[146:149], v33 offset:56176
	v_fmac_f32_e32 v124, 0x3377d1cf, v118
	s_waitcnt lgkmcnt(3)
	v_fma_f32 v125, v32, v110, v29
	v_fmac_f32_e32 v125, v95, v111
	v_fmac_f32_e32 v125, v96, v112
	v_fmac_f32_e32 v125, v97, v113
	s_waitcnt lgkmcnt(2)
	v_fmac_f32_e32 v125, v37, v114
	v_fmac_f32_e32 v125, v34, v115
	v_fmac_f32_e32 v125, v35, v116
	v_fmac_f32_e32 v125, v36, v117
	s_waitcnt lgkmcnt(1)
	v_fmac_f32_e32 v125, v30, v142
	v_fmac_f32_e32 v125, v31, v143
	v_pk_mul_f32 v[110:111], v[22:23], v[144:145]
	v_cndmask_b32_e32 v113, 0, v161, vcc
	v_add_f32_e32 v110, v125, v110
	v_add_f32_e32 v112, v110, v111
	s_waitcnt lgkmcnt(0)
	v_pk_mul_f32 v[110:111], v[24:25], v[146:147]
	v_fmac_f32_e32 v124, 0x3f317217, v118
	v_add_f32_e32 v110, v112, v110
	v_add_f32_e32 v112, v110, v111
	v_pk_mul_f32 v[110:111], v[26:27], v[148:149]
	v_cmp_lt_f32_e64 s[40:41], |v118|, s45
	v_add_f32_e32 v110, v112, v110
	v_add_f32_e32 v110, v110, v111
	v_mul_f32_e64 v111, |v110|, s46
	v_exp_f32_e32 v111, v111
	v_cndmask_b32_e64 v112, v118, v124, s[40:41]
	v_max_f32_e64 v124, -v110, 0
	v_add_f32_e32 v111, 1.0, v111
	v_cmp_gt_f32_e32 vcc, s84, v111
	s_nop 1
	v_cndmask_b32_e64 v114, 0, 32, vcc
	v_ldexp_f32 v111, v111, v114
	v_log_f32_e32 v118, v111
	v_sub_f32_e32 v111, v112, v113
	v_add_f32_e32 v123, v123, v111
	ds_read_b128 v[110:113], v33 offset:56192
	v_mul_f32_e32 v114, 0x3f317217, v118
	v_fma_f32 v125, v118, s44, -v114
	ds_read_b128 v[114:117], v33 offset:56208
	ds_read_b128 v[142:145], v33 offset:56224
	ds_read_b128 v[146:149], v33 offset:56240
	v_fmac_f32_e32 v125, 0x3377d1cf, v118
	s_waitcnt lgkmcnt(3)
	v_fma_f32 v126, v32, v110, v29
	v_fmac_f32_e32 v126, v95, v111
	v_fmac_f32_e32 v126, v96, v112
	v_fmac_f32_e32 v126, v97, v113
	s_waitcnt lgkmcnt(2)
	v_fmac_f32_e32 v126, v37, v114
	v_fmac_f32_e32 v126, v34, v115
	v_fmac_f32_e32 v126, v35, v116
	v_fmac_f32_e32 v126, v36, v117
	s_waitcnt lgkmcnt(1)
	v_fmac_f32_e32 v126, v30, v142
	v_fmac_f32_e32 v126, v31, v143
	v_pk_mul_f32 v[110:111], v[22:23], v[144:145]
	v_cndmask_b32_e32 v113, 0, v161, vcc
	v_add_f32_e32 v110, v126, v110
	v_add_f32_e32 v112, v110, v111
	s_waitcnt lgkmcnt(0)
	v_pk_mul_f32 v[110:111], v[24:25], v[146:147]
	v_fmac_f32_e32 v125, 0x3f317217, v118
	v_add_f32_e32 v110, v112, v110
	v_add_f32_e32 v112, v110, v111
	v_pk_mul_f32 v[110:111], v[26:27], v[148:149]
	v_cmp_lt_f32_e64 s[40:41], |v118|, s45
	v_add_f32_e32 v110, v112, v110
	v_add_f32_e32 v110, v110, v111
	v_mul_f32_e64 v111, |v110|, s46
	v_exp_f32_e32 v111, v111
	v_cndmask_b32_e64 v112, v118, v125, s[40:41]
	v_max_f32_e64 v125, -v110, 0
	v_add_f32_e32 v111, 1.0, v111
	v_cmp_gt_f32_e32 vcc, s84, v111
	s_nop 1
	v_cndmask_b32_e64 v114, 0, 32, vcc
	v_ldexp_f32 v111, v111, v114
	v_log_f32_e32 v118, v111
	v_sub_f32_e32 v111, v112, v113
	v_add_f32_e32 v124, v124, v111
	ds_read_b128 v[110:113], v33 offset:56256
	v_mul_f32_e32 v114, 0x3f317217, v118
	v_fma_f32 v126, v118, s44, -v114
	ds_read_b128 v[114:117], v33 offset:56272
	v_fmac_f32_e32 v126, 0x3377d1cf, v118
	s_waitcnt lgkmcnt(1)
	v_fmac_f32_e32 v29, v32, v110
	v_fmac_f32_e32 v29, v95, v111
	v_fmac_f32_e32 v29, v96, v112
	v_fmac_f32_e32 v29, v97, v113
	ds_read_b128 v[110:113], v33 offset:56288
	s_waitcnt lgkmcnt(1)
	v_fmac_f32_e32 v29, v37, v114
	v_fmac_f32_e32 v29, v34, v115
	v_fmac_f32_e32 v29, v35, v116
	ds_read_b128 v[32:35], v33 offset:56304
	v_fmac_f32_e32 v29, v36, v117
	s_waitcnt lgkmcnt(1)
	v_fmac_f32_e32 v29, v30, v110
	v_fmac_f32_e32 v29, v31, v111
	v_pk_mul_f32 v[22:23], v[22:23], v[112:113]
	v_lshlrev_b32_e32 v110, 2, v28
	v_add_f32_e32 v22, v29, v22
	v_add_f32_e32 v29, v22, v23
	s_waitcnt lgkmcnt(0)
	v_pk_mul_f32 v[22:23], v[24:25], v[32:33]
	v_lshl_or_b32 v96, s6, 2, v110
	v_add_f32_e32 v22, v29, v22
	v_add_f32_e32 v24, v22, v23
	v_pk_mul_f32 v[22:23], v[26:27], v[34:35]
	s_mov_b32 s6, 0xbd800000
	v_add_f32_e32 v22, v24, v22
	v_add_f32_e32 v22, v22, v23
	v_mul_f32_e64 v23, |v22|, s46
	v_exp_f32_e32 v23, v23
	v_cndmask_b32_e32 v25, 0, v161, vcc
	v_fma_f32 v36, v99, s6, 0
	v_fmamk_f32 v37, v101, 0xbd800000, v36
	v_add_f32_e32 v23, 1.0, v23
	v_cmp_gt_f32_e32 vcc, s84, v23
	v_fmamk_f32 v34, v103, 0xbd800000, v37
	v_fmamk_f32 v35, v105, 0xbd800000, v34
	v_cndmask_b32_e64 v26, 0, 32, vcc
	v_ldexp_f32 v23, v23, v26
	v_log_f32_e32 v23, v23
	v_fmac_f32_e32 v126, 0x3f317217, v118
	v_cmp_lt_f32_e64 s[40:41], |v118|, s45
	v_fmamk_f32 v32, v106, 0xbd800000, v35
	v_fmamk_f32 v33, v107, 0xbd800000, v32
	v_cndmask_b32_e64 v24, v118, v126, s[40:41]
	v_sub_f32_e32 v24, v24, v25
	v_fmamk_f32 v30, v108, 0xbd800000, v33
	v_add_f32_e32 v95, v125, v24
	v_mul_f32_e32 v24, 0x3f317217, v23
	v_fmamk_f32 v31, v109, 0xbd800000, v30
	v_fma_f32 v24, v23, s44, -v24
	v_fmamk_f32 v28, v119, 0xbd800000, v31
	v_fmac_f32_e32 v24, 0x3377d1cf, v23
	v_fmamk_f32 v29, v120, 0xbd800000, v28
	v_fmac_f32_e32 v24, 0x3f317217, v23
	v_cmp_lt_f32_e64 s[40:41], |v23|, s45
	v_fmamk_f32 v26, v121, 0xbd800000, v29
	v_fmamk_f32 v27, v122, 0xbd800000, v26
	v_cndmask_b32_e64 v23, v23, v24, s[40:41]
	v_cndmask_b32_e32 v24, 0, v161, vcc
	v_sub_f32_e32 v23, v23, v24
	v_fmamk_f32 v24, v123, 0xbd800000, v27
	v_max_f32_e64 v22, -v22, 0
	v_fmamk_f32 v25, v124, 0xbd800000, v24
	v_add_f32_e32 v23, v22, v23
	v_fmamk_f32 v22, v95, 0xbd800000, v25
	v_fmamk_f32 v23, v23, 0xbd800000, v22
	ds_write_b32 v96, v23 offset:59392
	s_waitcnt lgkmcnt(0)
	s_barrier
	ds_read2st64_b32 v[96:97], v110 offset0:232 offset1:233
	ds_read2st64_b32 v[106:107], v110 offset0:234 offset1:235
	s_cselect_b64 vcc, -1, 0
	s_cmp_gt_i32 s42, 1
	s_mov_b64 s[6:7], 0
	s_waitcnt lgkmcnt(1)
	v_add_f32_e32 v95, 0, v96
	v_cndmask_b32_e32 v95, 0, v95, vcc
	v_add_f32_e32 v96, v97, v95
	s_cselect_b64 vcc, -1, 0
	s_cmp_gt_i32 s42, 2
	v_cndmask_b32_e32 v95, v95, v96, vcc
	s_waitcnt lgkmcnt(0)
	v_add_f32_e32 v96, v106, v95
	s_cselect_b64 vcc, -1, 0
	s_cmp_gt_i32 s42, 3
	v_cndmask_b32_e32 v95, v95, v96, vcc
	v_add_f32_e32 v96, v107, v95
	s_cselect_b64 vcc, -1, 0
	v_cndmask_b32_e32 v96, v95, v96, vcc
	v_pk_add_f32 v[22:23], v[22:23], v[96:97] op_sel_hi:[1,0]
	v_pk_add_f32 v[24:25], v[24:25], v[96:97] op_sel_hi:[1,0]
	v_pk_add_f32 v[26:27], v[26:27], v[96:97] op_sel_hi:[1,0]
	v_pk_add_f32 v[28:29], v[28:29], v[96:97] op_sel_hi:[1,0]
	v_pk_add_f32 v[30:31], v[30:31], v[96:97] op_sel_hi:[1,0]
	v_pk_add_f32 v[32:33], v[32:33], v[96:97] op_sel_hi:[1,0]
	v_pk_add_f32 v[34:35], v[34:35], v[96:97] op_sel_hi:[1,0]
	v_pk_add_f32 v[36:37], v[36:37], v[96:97] op_sel_hi:[1,0]

.LBB0_219:
	s_mul_hi_i32 s6, s18, 0x66666667
	s_lshr_b32 s7, s6, 31
	s_ashr_i32 s6, s6, 8
	s_add_i32 s6, s6, s7
	s_ashr_i32 s7, s18, 31
	s_lshr_b32 s7, s7, 26
	s_add_i32 s7, s18, s7
	s_ashr_i32 s7, s7, 6
	s_mul_hi_i32 s20, s7, 0x66666667
	s_lshr_b32 s21, s20, 31
	s_ashr_i32 s20, s20, 2
	s_add_i32 s20, s20, s21
	s_mul_i32 s20, s20, 10
	s_sub_i32 s56, s7, s20
	s_and_b32 s21, s18, 63
	s_waitcnt vmcnt(0)
	v_mov_b32_e32 v37, v154
	s_ashr_i32 s7, s6, 31
	s_lshl_b64 s[34:35], s[6:7], 12
	v_readfirstlane_b32 s20, v37
	s_lshl_b32 s36, s21, 6
	s_or_b32 s34, s34, s36
	s_ashr_i32 s36, s20, 2
	s_and_b32 s54, s36, -16
	s_ashr_i32 s55, s54, 31
	s_add_u32 s39, s34, s54
	s_addc_u32 s40, s35, s55
	s_lshl_b32 s34, s56, 6
	s_ashr_i32 s35, s34, 31
	s_lshl_b64 s[36:37], s[34:35], 1
	v_and_b32_e32 v28, 63, v37
	s_add_u32 s36, s48, s36
	s_addc_u32 s37, s49, s37
	v_lshlrev_b32_e32 v0, 1, v28
	v_lshl_add_u64 v[2:3], s[36:37], 0, v[0:1]
	s_mulk_i32 s40, 0x500
	v_mad_u64_u32 v[2:3], s[36:37], s39, v164, v[2:3]
	v_add_u32_e32 v3, s40, v3
	v_add_co_u32_e32 v4, vcc, s88, v2
	s_movk_i32 s35, 0x2000
	s_nop 0
	v_addc_co_u32_e32 v5, vcc, 0, v3, vcc
	v_add_co_u32_e32 v6, vcc, s35, v2
	s_mul_i32 s38, s6, 10
	s_nop 0
	v_addc_co_u32_e32 v7, vcc, 0, v3, vcc
	s_movk_i32 s35, 0x3000
	v_add_co_u32_e32 v8, vcc, s35, v2
	s_add_i32 s36, s38, s56
	s_nop 0
	v_addc_co_u32_e32 v9, vcc, 0, v3, vcc
	s_ashr_i32 s37, s36, 31
	s_waitcnt lgkmcnt(0)
	s_barrier
	global_load_ushort v45, v[2:3], off
	global_load_ushort v46, v[2:3], off offset:1280
	global_load_ushort v41, v[2:3], off offset:2560
	global_load_ushort v42, v[2:3], off offset:3840
	v_add_co_u32_e32 v2, vcc, s47, v2
	v_ashrrev_i32_e32 v10, 3, v37
	v_lshlrev_b32_e32 v0, 3, v37
	s_lshl_b64 s[52:53], s[36:37], 6
	s_lshl_b32 s35, s21, 7
	global_load_ushort v43, v[4:5], off offset:1024
	global_load_ushort v44, v[4:5], off offset:2304
	global_load_ushort v39, v[4:5], off offset:3584
	global_load_ushort v40, v[6:7], off offset:768
	global_load_ushort v36, v[6:7], off offset:2048
	global_load_ushort v38, v[6:7], off offset:3328
	global_load_ushort v34, v[8:9], off offset:512
	global_load_ushort v35, v[8:9], off offset:1792
	v_addc_co_u32_e32 v3, vcc, 0, v3, vcc
	v_and_b32_e32 v29, 56, v0
	v_ashrrev_i32_e32 v11, 31, v10
	s_add_u32 s36, s50, s35
	global_load_ushort v32, v[8:9], off offset:3072
	global_load_ushort v33, v[2:3], off offset:256
	global_load_ushort v30, v[2:3], off offset:1536
	global_load_ushort v31, v[2:3], off offset:2816
	v_lshl_add_u64 v[2:3], s[52:53], 0, v[10:11]
	s_addc_u32 s37, s51, 0
	v_lshlrev_b32_e32 v0, 1, v29
	v_lshl_add_u64 v[4:5], s[36:37], 0, v[0:1]
	v_lshlrev_b64 v[2:3], 13, v[2:3]
	v_lshl_add_u64 v[2:3], v[4:5], 0, v[2:3]
	v_add_co_u32_e32 v6, vcc, 0x40000, v2
	v_mov_b32_e32 v0, v154
	s_nop 0
	v_addc_co_u32_e32 v7, vcc, 0, v3, vcc
	global_load_dwordx4 v[2:5], v[2:3], off
	s_nop 0
	global_load_dwordx4 v[6:9], v[6:7], off
	s_mov_b64 s[36:37], -1
	v_readfirstlane_b32 s40, v0
	s_ashr_i32 s35, s40, 6
	s_cmp_gt_i32 s56, 5
	s_cbranch_scc0 .LBB0_221
	s_lshl_b64 s[6:7], s[6:7], 18
	s_add_u32 s6, s24, s6
	s_addc_u32 s7, s25, s7
	s_lshl_b32 s36, s21, 12
	s_add_u32 s6, s6, s36
	v_lshlrev_b32_e32 v12, 2, v0
	s_addc_u32 s7, s7, 0
	v_ashrrev_i32_e32 v13, 31, v12
	v_lshl_add_u64 v[12:13], v[12:13], 2, s[6:7]
	global_load_dwordx4 v[12:15], v[12:13], off
	v_and_b32_e32 v11, 63, v0
	v_lshlrev_b32_e32 v0, 4, v0
	s_add_i32 s6, s34, 0xfffffe80
	s_mov_b64 s[36:37], 0
	s_waitcnt vmcnt(0)
	ds_write_b128 v0, v[12:15] offset:18432
	v_or_b32_e32 v0, s6, v11
	v_lshlrev_b64 v[48:49], 2, v[0:1]
	v_lshl_add_u64 v[12:13], s[26:27], 0, v[48:49]
	v_add_co_u32_e32 v14, vcc, s88, v12
	s_movk_i32 s6, 0x2000
	s_nop 0
	v_addc_co_u32_e32 v15, vcc, 0, v13, vcc
	v_add_co_u32_e32 v50, vcc, s6, v12
	s_movk_i32 s6, 0x3000
	s_nop 0
	v_addc_co_u32_e32 v51, vcc, 0, v13, vcc
	global_load_dword v23, v[12:13], off
	global_load_dword v24, v[12:13], off offset:1024
	global_load_dword v25, v[12:13], off offset:2048
	global_load_dword v26, v[12:13], off offset:3072
	global_load_dword v19, v[50:51], off offset:-4096
	global_load_dword v20, v[14:15], off offset:1024
	global_load_dword v21, v[14:15], off offset:2048
	global_load_dword v22, v[14:15], off offset:3072
	global_load_dword v0, v[50:51], off
	global_load_dword v18, v[50:51], off offset:1024
	global_load_dword v16, v[50:51], off offset:2048
	global_load_dword v17, v[50:51], off offset:3072
	v_add_co_u32_e32 v50, vcc, s6, v12
	v_lshl_add_u64 v[48:49], s[22:23], 0, v[48:49]
	s_nop 0
	v_addc_co_u32_e32 v51, vcc, 0, v13, vcc
	global_load_dword v14, v[50:51], off
	global_load_dword v15, v[50:51], off offset:1024
	global_load_dword v12, v[50:51], off offset:2048
	global_load_dword v13, v[50:51], off offset:3072
	global_load_dword v47, v[48:49], off
	s_lshl_b32 s6, s35, 10
	v_mov_b32_e32 v48, s6
	s_waitcnt lgkmcnt(0)
	s_barrier
	ds_read_b128 v[50:53], v48 offset:18432
	ds_read_b128 v[54:57], v48 offset:18448
	ds_read_b128 v[58:61], v48 offset:18464
	ds_read_b128 v[62:65], v48 offset:18480
	s_and_b32 s6, s40, 0x3fffffc0
	v_lshlrev_b32_e32 v11, 2, v11
	s_cmp_gt_i32 s35, 0
	s_waitcnt vmcnt(0) lgkmcnt(3)
	v_fma_f32 v27, v23, v50, v47
	v_fmac_f32_e32 v27, v24, v51
	v_fmac_f32_e32 v27, v25, v52
	v_fmac_f32_e32 v27, v26, v53
	s_waitcnt lgkmcnt(2)
	v_fmac_f32_e32 v27, v19, v54
	v_fmac_f32_e32 v27, v20, v55
	v_fmac_f32_e32 v27, v21, v56
	v_fmac_f32_e32 v27, v22, v57
	s_waitcnt lgkmcnt(1)
	v_fmac_f32_e32 v27, v0, v58
	v_fmac_f32_e32 v27, v18, v59
	v_pk_mul_f32 v[50:51], v[16:17], v[60:61]
	s_nop 0
	v_add_f32_e32 v27, v27, v50
	v_add_f32_e32 v27, v27, v51
	s_waitcnt lgkmcnt(0)
	v_pk_mul_f32 v[50:51], v[14:15], v[62:63]
	s_nop 0
	v_add_f32_e32 v27, v27, v50
	v_add_f32_e32 v27, v27, v51
	v_pk_mul_f32 v[50:51], v[12:13], v[64:65]
	s_nop 0
	v_add_f32_e32 v27, v27, v50
	v_add_f32_e32 v27, v27, v51
	v_max_f32_e64 v49, -v27, 0
	v_mul_f32_e64 v27, |v27|, s46
	v_exp_f32_e32 v27, v27
	s_nop 0
	v_add_f32_e32 v27, 1.0, v27
	v_cmp_gt_f32_e32 vcc, s84, v27
	s_nop 1
	v_cndmask_b32_e64 v50, 0, 32, vcc
	v_ldexp_f32 v27, v27, v50
	v_log_f32_e32 v27, v27
	s_nop 0
	v_mul_f32_e32 v50, 0x3f317217, v27
	v_fma_f32 v50, v27, s44, -v50
	v_fmac_f32_e32 v50, 0x3377d1cf, v27
	v_fmac_f32_e32 v50, 0x3f317217, v27
	v_cmp_lt_f32_e64 s[38:39], |v27|, s45
	s_nop 1
	v_cndmask_b32_e64 v27, v27, v50, s[38:39]
	v_cndmask_b32_e32 v50, 0, v161, vcc
	v_sub_f32_e32 v27, v27, v50
	ds_read_b128 v[50:53], v48 offset:18496
	ds_read_b128 v[68:71], v48 offset:18512
	ds_read_b128 v[72:75], v48 offset:18528
	ds_read_b128 v[76:79], v48 offset:18544
	v_add_f32_e32 v27, v49, v27
	s_waitcnt lgkmcnt(3)
	v_fma_f32 v49, v23, v50, v47
	v_fmac_f32_e32 v49, v24, v51
	v_fmac_f32_e32 v49, v25, v52
	v_fmac_f32_e32 v49, v26, v53
	s_waitcnt lgkmcnt(2)
	v_fmac_f32_e32 v49, v19, v68
	v_fmac_f32_e32 v49, v20, v69
	v_fmac_f32_e32 v49, v21, v70
	v_fmac_f32_e32 v49, v22, v71
	s_waitcnt lgkmcnt(1)
	v_fmac_f32_e32 v49, v0, v72
	v_fmac_f32_e32 v49, v18, v73
	v_pk_mul_f32 v[50:51], v[16:17], v[74:75]
	s_nop 0
	v_add_f32_e32 v49, v49, v50
	v_add_f32_e32 v49, v49, v51
	s_waitcnt lgkmcnt(0)
	v_pk_mul_f32 v[50:51], v[14:15], v[76:77]
	s_nop 0
	v_add_f32_e32 v49, v49, v50
	v_add_f32_e32 v49, v49, v51
	v_pk_mul_f32 v[50:51], v[12:13], v[78:79]
	s_nop 0
	v_add_f32_e32 v49, v49, v50
	v_add_f32_e32 v49, v49, v51
	v_max_f32_e64 v50, -v49, 0
	v_mul_f32_e64 v49, |v49|, s46
	v_exp_f32_e32 v49, v49
	s_nop 0
	v_add_f32_e32 v49, 1.0, v49
	v_cmp_gt_f32_e32 vcc, s84, v49
	s_nop 1
	v_cndmask_b32_e64 v51, 0, 32, vcc
	v_ldexp_f32 v49, v49, v51
	v_log_f32_e32 v49, v49
	s_nop 0
	v_mul_f32_e32 v51, 0x3f317217, v49
	v_fma_f32 v51, v49, s44, -v51
	v_fmac_f32_e32 v51, 0x3377d1cf, v49
	v_fmac_f32_e32 v51, 0x3f317217, v49
	v_cmp_lt_f32_e64 s[38:39], |v49|, s45
	s_nop 1
	v_cndmask_b32_e64 v49, v49, v51, s[38:39]
	v_cndmask_b32_e32 v51, 0, v161, vcc
	v_sub_f32_e32 v49, v49, v51
	v_add_f32_e32 v49, v50, v49
	ds_read_b128 v[50:53], v48 offset:18560
	ds_read_b128 v[68:71], v48 offset:18576
	ds_read_b128 v[72:75], v48 offset:18592
	ds_read_b128 v[76:79], v48 offset:18608
	s_waitcnt lgkmcnt(3)
	v_fma_f32 v54, v23, v50, v47
	v_fmac_f32_e32 v54, v24, v51
	v_fmac_f32_e32 v54, v25, v52
	v_fmac_f32_e32 v54, v26, v53
	s_waitcnt lgkmcnt(2)
	v_fmac_f32_e32 v54, v19, v68
	v_fmac_f32_e32 v54, v20, v69
	v_fmac_f32_e32 v54, v21, v70
	v_fmac_f32_e32 v54, v22, v71
	s_waitcnt lgkmcnt(1)
	v_fmac_f32_e32 v54, v0, v72
	v_fmac_f32_e32 v54, v18, v73
	v_pk_mul_f32 v[50:51], v[16:17], v[74:75]
	s_nop 0
	v_add_f32_e32 v50, v54, v50
	v_add_f32_e32 v54, v50, v51
	s_waitcnt lgkmcnt(0)
	v_pk_mul_f32 v[50:51], v[14:15], v[76:77]
	s_nop 0
	v_add_f32_e32 v50, v54, v50
	v_add_f32_e32 v54, v50, v51
	v_pk_mul_f32 v[50:51], v[12:13], v[78:79]
	s_nop 0
	v_add_f32_e32 v50, v54, v50
	v_add_f32_e32 v50, v50, v51
	v_max_f32_e64 v51, -v50, 0
	v_mul_f32_e64 v50, |v50|, s46
	v_exp_f32_e32 v50, v50
	s_nop 0
	v_add_f32_e32 v50, 1.0, v50
	v_cmp_gt_f32_e32 vcc, s84, v50
	s_nop 1
	v_cndmask_b32_e64 v52, 0, 32, vcc
	v_ldexp_f32 v50, v50, v52
	v_log_f32_e32 v50, v50
	s_nop 0
	v_mul_f32_e32 v52, 0x3f317217, v50
	v_fma_f32 v52, v50, s44, -v52
	v_fmac_f32_e32 v52, 0x3377d1cf, v50
	v_fmac_f32_e32 v52, 0x3f317217, v50
	v_cmp_lt_f32_e64 s[38:39], |v50|, s45
	s_nop 1
	v_cndmask_b32_e64 v50, v50, v52, s[38:39]
	v_cndmask_b32_e32 v52, 0, v161, vcc
	v_sub_f32_e32 v50, v50, v52
	ds_read_b128 v[52:55], v48 offset:18624
	ds_read_b128 v[68:71], v48 offset:18640
	ds_read_b128 v[72:75], v48 offset:18656
	ds_read_b128 v[76:79], v48 offset:18672
	v_add_f32_e32 v50, v51, v50
	s_waitcnt lgkmcnt(3)
	v_fma_f32 v51, v23, v52, v47
	v_fmac_f32_e32 v51, v24, v53
	v_fmac_f32_e32 v51, v25, v54
	v_fmac_f32_e32 v51, v26, v55
	s_waitcnt lgkmcnt(2)
	v_fmac_f32_e32 v51, v19, v68
	v_fmac_f32_e32 v51, v20, v69
	v_fmac_f32_e32 v51, v21, v70
	v_fmac_f32_e32 v51, v22, v71
	s_waitcnt lgkmcnt(1)
	v_fmac_f32_e32 v51, v0, v72
	v_fmac_f32_e32 v51, v18, v73
	v_pk_mul_f32 v[52:53], v[16:17], v[74:75]
	s_nop 0
	v_add_f32_e32 v51, v51, v52
	v_add_f32_e32 v51, v51, v53
	s_waitcnt lgkmcnt(0)
	v_pk_mul_f32 v[52:53], v[14:15], v[76:77]
	s_nop 0
	v_add_f32_e32 v51, v51, v52
	v_add_f32_e32 v51, v51, v53
	v_pk_mul_f32 v[52:53], v[12:13], v[78:79]
	s_nop 0
	v_add_f32_e32 v51, v51, v52
	v_add_f32_e32 v51, v51, v53
	v_max_f32_e64 v52, -v51, 0
	v_mul_f32_e64 v51, |v51|, s46
	v_exp_f32_e32 v51, v51
	s_nop 0
	v_add_f32_e32 v51, 1.0, v51
	v_cmp_gt_f32_e32 vcc, s84, v51
	s_nop 1
	v_cndmask_b32_e64 v53, 0, 32, vcc
	v_ldexp_f32 v51, v51, v53
	v_log_f32_e32 v51, v51
	s_nop 0
	v_mul_f32_e32 v53, 0x3f317217, v51
	v_fma_f32 v53, v51, s44, -v53
	v_fmac_f32_e32 v53, 0x3377d1cf, v51
	v_fmac_f32_e32 v53, 0x3f317217, v51
	v_cmp_lt_f32_e64 s[38:39], |v51|, s45
	s_nop 1
	v_cndmask_b32_e64 v51, v51, v53, s[38:39]
	v_cndmask_b32_e32 v53, 0, v161, vcc
	v_sub_f32_e32 v51, v51, v53
	v_add_f32_e32 v51, v52, v51
	ds_read_b128 v[52:55], v48 offset:18688
	ds_read_b128 v[68:71], v48 offset:18704
	ds_read_b128 v[72:75], v48 offset:18720
	ds_read_b128 v[76:79], v48 offset:18736
	s_waitcnt lgkmcnt(3)
	v_fma_f32 v56, v23, v52, v47
	v_fmac_f32_e32 v56, v24, v53
	v_fmac_f32_e32 v56, v25, v54
	v_fmac_f32_e32 v56, v26, v55
	s_waitcnt lgkmcnt(2)
	v_fmac_f32_e32 v56, v19, v68
	v_fmac_f32_e32 v56, v20, v69
	v_fmac_f32_e32 v56, v21, v70
	v_fmac_f32_e32 v56, v22, v71
	s_waitcnt lgkmcnt(1)
	v_fmac_f32_e32 v56, v0, v72
	v_fmac_f32_e32 v56, v18, v73
	v_pk_mul_f32 v[52:53], v[16:17], v[74:75]
	s_nop 0
	v_add_f32_e32 v52, v56, v52
	v_add_f32_e32 v56, v52, v53
	s_waitcnt lgkmcnt(0)
	v_pk_mul_f32 v[52:53], v[14:15], v[76:77]
	s_nop 0
	v_add_f32_e32 v52, v56, v52
	v_add_f32_e32 v56, v52, v53
	v_pk_mul_f32 v[52:53], v[12:13], v[78:79]
	s_nop 0
	v_add_f32_e32 v52, v56, v52
	v_add_f32_e32 v52, v52, v53
	v_max_f32_e64 v53, -v52, 0
	v_mul_f32_e64 v52, |v52|, s46
	v_exp_f32_e32 v52, v52
	s_nop 0
	v_add_f32_e32 v52, 1.0, v52
	v_cmp_gt_f32_e32 vcc, s84, v52
	s_nop 1
	v_cndmask_b32_e64 v54, 0, 32, vcc
	v_ldexp_f32 v52, v52, v54
	v_log_f32_e32 v52, v52
	s_nop 0
	v_mul_f32_e32 v54, 0x3f317217, v52
	v_fma_f32 v54, v52, s44, -v54
	v_fmac_f32_e32 v54, 0x3377d1cf, v52
	v_fmac_f32_e32 v54, 0x3f317217, v52
	v_cmp_lt_f32_e64 s[38:39], |v52|, s45
	s_nop 1
	v_cndmask_b32_e64 v52, v52, v54, s[38:39]
	v_cndmask_b32_e32 v54, 0, v161, vcc
	v_sub_f32_e32 v52, v52, v54
	ds_read_b128 v[54:57], v48 offset:18752
	ds_read_b128 v[68:71], v48 offset:18768
	ds_read_b128 v[72:75], v48 offset:18784
	ds_read_b128 v[76:79], v48 offset:18800
	v_add_f32_e32 v52, v53, v52
	s_waitcnt lgkmcnt(3)
	v_fma_f32 v53, v23, v54, v47
	v_fmac_f32_e32 v53, v24, v55
	v_fmac_f32_e32 v53, v25, v56
	v_fmac_f32_e32 v53, v26, v57
	s_waitcnt lgkmcnt(2)
	v_fmac_f32_e32 v53, v19, v68
	v_fmac_f32_e32 v53, v20, v69
	v_fmac_f32_e32 v53, v21, v70
	v_fmac_f32_e32 v53, v22, v71
	s_waitcnt lgkmcnt(1)
	v_fmac_f32_e32 v53, v0, v72
	v_fmac_f32_e32 v53, v18, v73
	v_pk_mul_f32 v[54:55], v[16:17], v[74:75]
	s_nop 0
	v_add_f32_e32 v53, v53, v54
	v_add_f32_e32 v53, v53, v55
	s_waitcnt lgkmcnt(0)
	v_pk_mul_f32 v[54:55], v[14:15], v[76:77]
	s_nop 0
	v_add_f32_e32 v53, v53, v54
	v_add_f32_e32 v53, v53, v55
	v_pk_mul_f32 v[54:55], v[12:13], v[78:79]
	s_nop 0
	v_add_f32_e32 v53, v53, v54
	v_add_f32_e32 v53, v53, v55
	v_max_f32_e64 v54, -v53, 0
	v_mul_f32_e64 v53, |v53|, s46
	v_exp_f32_e32 v53, v53
	s_nop 0
	v_add_f32_e32 v53, 1.0, v53
	v_cmp_gt_f32_e32 vcc, s84, v53
	s_nop 1
	v_cndmask_b32_e64 v55, 0, 32, vcc
	v_ldexp_f32 v53, v53, v55
	v_log_f32_e32 v53, v53
	s_nop 0
	v_mul_f32_e32 v55, 0x3f317217, v53
	v_fma_f32 v55, v53, s44, -v55
	v_fmac_f32_e32 v55, 0x3377d1cf, v53
	v_fmac_f32_e32 v55, 0x3f317217, v53
	v_cmp_lt_f32_e64 s[38:39], |v53|, s45
	s_nop 1
	v_cndmask_b32_e64 v53, v53, v55, s[38:39]
	v_cndmask_b32_e32 v55, 0, v161, vcc
	v_sub_f32_e32 v53, v53, v55
	v_add_f32_e32 v53, v54, v53
	ds_read_b128 v[54:57], v48 offset:18816
	ds_read_b128 v[68:71], v48 offset:18832
	ds_read_b128 v[72:75], v48 offset:18848
	ds_read_b128 v[76:79], v48 offset:18864
	s_waitcnt lgkmcnt(3)
	v_fma_f32 v58, v23, v54, v47
	v_fmac_f32_e32 v58, v24, v55
	v_fmac_f32_e32 v58, v25, v56
	v_fmac_f32_e32 v58, v26, v57
	s_waitcnt lgkmcnt(2)
	v_fmac_f32_e32 v58, v19, v68
	v_fmac_f32_e32 v58, v20, v69
	v_fmac_f32_e32 v58, v21, v70
	v_fmac_f32_e32 v58, v22, v71
	s_waitcnt lgkmcnt(1)
	v_fmac_f32_e32 v58, v0, v72
	v_fmac_f32_e32 v58, v18, v73
	v_pk_mul_f32 v[54:55], v[16:17], v[74:75]
	s_nop 0
	v_add_f32_e32 v54, v58, v54
	v_add_f32_e32 v58, v54, v55
	s_waitcnt lgkmcnt(0)
	v_pk_mul_f32 v[54:55], v[14:15], v[76:77]
	s_nop 0
	v_add_f32_e32 v54, v58, v54
	v_add_f32_e32 v58, v54, v55
	v_pk_mul_f32 v[54:55], v[12:13], v[78:79]
	s_nop 0
	v_add_f32_e32 v54, v58, v54
	v_add_f32_e32 v54, v54, v55
	v_max_f32_e64 v55, -v54, 0
	v_mul_f32_e64 v54, |v54|, s46
	v_exp_f32_e32 v54, v54
	s_nop 0
	v_add_f32_e32 v54, 1.0, v54
	v_cmp_gt_f32_e32 vcc, s84, v54
	s_nop 1
	v_cndmask_b32_e64 v56, 0, 32, vcc
	v_ldexp_f32 v54, v54, v56
	v_log_f32_e32 v54, v54
	s_nop 0
	v_mul_f32_e32 v56, 0x3f317217, v54
	v_fma_f32 v56, v54, s44, -v56
	v_fmac_f32_e32 v56, 0x3377d1cf, v54
	v_fmac_f32_e32 v56, 0x3f317217, v54
	v_cmp_lt_f32_e64 s[38:39], |v54|, s45
	s_nop 1
	v_cndmask_b32_e64 v54, v54, v56, s[38:39]
	v_cndmask_b32_e32 v56, 0, v161, vcc
	v_sub_f32_e32 v54, v54, v56
	ds_read_b128 v[56:59], v48 offset:18880
	ds_read_b128 v[68:71], v48 offset:18896
	ds_read_b128 v[72:75], v48 offset:18912
	ds_read_b128 v[76:79], v48 offset:18928
	v_add_f32_e32 v54, v55, v54
	s_waitcnt lgkmcnt(3)
	v_fma_f32 v55, v23, v56, v47
	v_fmac_f32_e32 v55, v24, v57
	v_fmac_f32_e32 v55, v25, v58
	v_fmac_f32_e32 v55, v26, v59
	s_waitcnt lgkmcnt(2)
	v_fmac_f32_e32 v55, v19, v68
	v_fmac_f32_e32 v55, v20, v69
	v_fmac_f32_e32 v55, v21, v70
	v_fmac_f32_e32 v55, v22, v71
	s_waitcnt lgkmcnt(1)
	v_fmac_f32_e32 v55, v0, v72
	v_fmac_f32_e32 v55, v18, v73
	v_pk_mul_f32 v[56:57], v[16:17], v[74:75]
	s_nop 0
	v_add_f32_e32 v55, v55, v56
	v_add_f32_e32 v55, v55, v57
	s_waitcnt lgkmcnt(0)
	v_pk_mul_f32 v[56:57], v[14:15], v[76:77]
	s_nop 0
	v_add_f32_e32 v55, v55, v56
	v_add_f32_e32 v55, v55, v57
	v_pk_mul_f32 v[56:57], v[12:13], v[78:79]
	s_nop 0
	v_add_f32_e32 v55, v55, v56
	v_add_f32_e32 v55, v55, v57
	v_max_f32_e64 v56, -v55, 0
	v_mul_f32_e64 v55, |v55|, s46
	v_exp_f32_e32 v55, v55
	s_nop 0
	v_add_f32_e32 v55, 1.0, v55
	v_cmp_gt_f32_e32 vcc, s84, v55
	s_nop 1
	v_cndmask_b32_e64 v57, 0, 32, vcc
	v_ldexp_f32 v55, v55, v57
	v_log_f32_e32 v55, v55
	s_nop 0
	v_mul_f32_e32 v57, 0x3f317217, v55
	v_fma_f32 v57, v55, s44, -v57
	v_fmac_f32_e32 v57, 0x3377d1cf, v55
	v_fmac_f32_e32 v57, 0x3f317217, v55
	v_cmp_lt_f32_e64 s[38:39], |v55|, s45
	s_nop 1
	v_cndmask_b32_e64 v55, v55, v57, s[38:39]
	v_cndmask_b32_e32 v57, 0, v161, vcc
	v_sub_f32_e32 v55, v55, v57
	v_add_f32_e32 v55, v56, v55
	ds_read_b128 v[56:59], v48 offset:18944
	ds_read_b128 v[68:71], v48 offset:18960
	ds_read_b128 v[72:75], v48 offset:18976
	ds_read_b128 v[76:79], v48 offset:18992
	s_waitcnt lgkmcnt(3)
	v_fma_f32 v60, v23, v56, v47
	v_fmac_f32_e32 v60, v24, v57
	v_fmac_f32_e32 v60, v25, v58
	v_fmac_f32_e32 v60, v26, v59
	s_waitcnt lgkmcnt(2)
	v_fmac_f32_e32 v60, v19, v68
	v_fmac_f32_e32 v60, v20, v69
	v_fmac_f32_e32 v60, v21, v70
	v_fmac_f32_e32 v60, v22, v71
	s_waitcnt lgkmcnt(1)
	v_fmac_f32_e32 v60, v0, v72
	v_fmac_f32_e32 v60, v18, v73
	v_pk_mul_f32 v[56:57], v[16:17], v[74:75]
	s_nop 0
	v_add_f32_e32 v56, v60, v56
	v_add_f32_e32 v60, v56, v57
	s_waitcnt lgkmcnt(0)
	v_pk_mul_f32 v[56:57], v[14:15], v[76:77]
	s_nop 0
	v_add_f32_e32 v56, v60, v56
	v_add_f32_e32 v60, v56, v57
	v_pk_mul_f32 v[56:57], v[12:13], v[78:79]
	s_nop 0
	v_add_f32_e32 v56, v60, v56
	v_add_f32_e32 v56, v56, v57
	v_max_f32_e64 v57, -v56, 0
	v_mul_f32_e64 v56, |v56|, s46
	v_exp_f32_e32 v56, v56
	s_nop 0
	v_add_f32_e32 v56, 1.0, v56
	v_cmp_gt_f32_e32 vcc, s84, v56
	s_nop 1
	v_cndmask_b32_e64 v58, 0, 32, vcc
	v_ldexp_f32 v56, v56, v58
	v_log_f32_e32 v56, v56
	s_nop 0
	v_mul_f32_e32 v58, 0x3f317217, v56
	v_fma_f32 v58, v56, s44, -v58
	v_fmac_f32_e32 v58, 0x3377d1cf, v56
	v_fmac_f32_e32 v58, 0x3f317217, v56
	v_cmp_lt_f32_e64 s[38:39], |v56|, s45
	s_nop 1
	v_cndmask_b32_e64 v56, v56, v58, s[38:39]
	v_cndmask_b32_e32 v58, 0, v161, vcc
	v_sub_f32_e32 v56, v56, v58
	ds_read_b128 v[58:61], v48 offset:19008
	ds_read_b128 v[68:71], v48 offset:19024
	ds_read_b128 v[72:75], v48 offset:19040
	ds_read_b128 v[76:79], v48 offset:19056
	v_add_f32_e32 v56, v57, v56
	s_waitcnt lgkmcnt(3)
	v_fma_f32 v57, v23, v58, v47
	v_fmac_f32_e32 v57, v24, v59
	v_fmac_f32_e32 v57, v25, v60
	v_fmac_f32_e32 v57, v26, v61
	s_waitcnt lgkmcnt(2)
	v_fmac_f32_e32 v57, v19, v68
	v_fmac_f32_e32 v57, v20, v69
	v_fmac_f32_e32 v57, v21, v70
	v_fmac_f32_e32 v57, v22, v71
	s_waitcnt lgkmcnt(1)
	v_fmac_f32_e32 v57, v0, v72
	v_fmac_f32_e32 v57, v18, v73
	v_pk_mul_f32 v[58:59], v[16:17], v[74:75]
	s_nop 0
	v_add_f32_e32 v57, v57, v58
	v_add_f32_e32 v57, v57, v59
	s_waitcnt lgkmcnt(0)
	v_pk_mul_f32 v[58:59], v[14:15], v[76:77]
	s_nop 0
	v_add_f32_e32 v57, v57, v58
	v_add_f32_e32 v57, v57, v59
	v_pk_mul_f32 v[58:59], v[12:13], v[78:79]
	s_nop 0
	v_add_f32_e32 v57, v57, v58
	v_add_f32_e32 v57, v57, v59
	v_max_f32_e64 v58, -v57, 0
	v_mul_f32_e64 v57, |v57|, s46
	v_exp_f32_e32 v57, v57
	s_nop 0
	v_add_f32_e32 v57, 1.0, v57
	v_cmp_gt_f32_e32 vcc, s84, v57
	s_nop 1
	v_cndmask_b32_e64 v59, 0, 32, vcc
	v_ldexp_f32 v57, v57, v59
	v_log_f32_e32 v57, v57
	s_nop 0
	v_mul_f32_e32 v59, 0x3f317217, v57
	v_fma_f32 v59, v57, s44, -v59
	v_fmac_f32_e32 v59, 0x3377d1cf, v57
	v_fmac_f32_e32 v59, 0x3f317217, v57
	v_cmp_lt_f32_e64 s[38:39], |v57|, s45
	s_nop 1
	v_cndmask_b32_e64 v57, v57, v59, s[38:39]
	v_cndmask_b32_e32 v59, 0, v161, vcc
	v_sub_f32_e32 v57, v57, v59
	v_add_f32_e32 v57, v58, v57
	ds_read_b128 v[58:61], v48 offset:19072
	ds_read_b128 v[68:71], v48 offset:19088
	ds_read_b128 v[72:75], v48 offset:19104
	ds_read_b128 v[76:79], v48 offset:19120
	s_waitcnt lgkmcnt(3)
	v_fma_f32 v62, v23, v58, v47
	v_fmac_f32_e32 v62, v24, v59
	v_fmac_f32_e32 v62, v25, v60
	v_fmac_f32_e32 v62, v26, v61
	s_waitcnt lgkmcnt(2)
	v_fmac_f32_e32 v62, v19, v68
	v_fmac_f32_e32 v62, v20, v69
	v_fmac_f32_e32 v62, v21, v70
	v_fmac_f32_e32 v62, v22, v71
	s_waitcnt lgkmcnt(1)
	v_fmac_f32_e32 v62, v0, v72
	v_fmac_f32_e32 v62, v18, v73
	v_pk_mul_f32 v[58:59], v[16:17], v[74:75]
	s_nop 0
	v_add_f32_e32 v58, v62, v58
	v_add_f32_e32 v62, v58, v59
	s_waitcnt lgkmcnt(0)
	v_pk_mul_f32 v[58:59], v[14:15], v[76:77]
	s_nop 0
	v_add_f32_e32 v58, v62, v58
	v_add_f32_e32 v62, v58, v59
	v_pk_mul_f32 v[58:59], v[12:13], v[78:79]
	s_nop 0
	v_add_f32_e32 v58, v62, v58
	v_add_f32_e32 v58, v58, v59
	v_max_f32_e64 v59, -v58, 0
	v_mul_f32_e64 v58, |v58|, s46
	v_exp_f32_e32 v58, v58
	s_nop 0
	v_add_f32_e32 v58, 1.0, v58
	v_cmp_gt_f32_e32 vcc, s84, v58
	s_nop 1
	v_cndmask_b32_e64 v60, 0, 32, vcc
	v_ldexp_f32 v58, v58, v60
	v_log_f32_e32 v58, v58
	s_nop 0
	v_mul_f32_e32 v60, 0x3f317217, v58
	v_fma_f32 v60, v58, s44, -v60
	v_fmac_f32_e32 v60, 0x3377d1cf, v58
	v_fmac_f32_e32 v60, 0x3f317217, v58
	v_cmp_lt_f32_e64 s[38:39], |v58|, s45
	s_nop 1
	v_cndmask_b32_e64 v58, v58, v60, s[38:39]
	v_cndmask_b32_e32 v60, 0, v161, vcc
	v_sub_f32_e32 v58, v58, v60
	ds_read_b128 v[60:63], v48 offset:19136
	ds_read_b128 v[68:71], v48 offset:19152
	ds_read_b128 v[72:75], v48 offset:19168
	ds_read_b128 v[76:79], v48 offset:19184
	v_add_f32_e32 v58, v59, v58
	s_waitcnt lgkmcnt(3)
	v_fma_f32 v59, v23, v60, v47
	v_fmac_f32_e32 v59, v24, v61
	v_fmac_f32_e32 v59, v25, v62
	v_fmac_f32_e32 v59, v26, v63
	s_waitcnt lgkmcnt(2)
	v_fmac_f32_e32 v59, v19, v68
	v_fmac_f32_e32 v59, v20, v69
	v_fmac_f32_e32 v59, v21, v70
	v_fmac_f32_e32 v59, v22, v71
	s_waitcnt lgkmcnt(1)
	v_fmac_f32_e32 v59, v0, v72
	v_fmac_f32_e32 v59, v18, v73
	v_pk_mul_f32 v[60:61], v[16:17], v[74:75]
	s_nop 0
	v_add_f32_e32 v59, v59, v60
	v_add_f32_e32 v59, v59, v61
	s_waitcnt lgkmcnt(0)
	v_pk_mul_f32 v[60:61], v[14:15], v[76:77]
	s_nop 0
	v_add_f32_e32 v59, v59, v60
	v_add_f32_e32 v59, v59, v61
	v_pk_mul_f32 v[60:61], v[12:13], v[78:79]
	s_nop 0
	v_add_f32_e32 v59, v59, v60
	v_add_f32_e32 v59, v59, v61
	v_max_f32_e64 v60, -v59, 0
	v_mul_f32_e64 v59, |v59|, s46
	v_exp_f32_e32 v59, v59
	s_nop 0
	v_add_f32_e32 v59, 1.0, v59
	v_cmp_gt_f32_e32 vcc, s84, v59
	s_nop 1
	v_cndmask_b32_e64 v61, 0, 32, vcc
	v_ldexp_f32 v59, v59, v61
	v_log_f32_e32 v59, v59
	s_nop 0
	v_mul_f32_e32 v61, 0x3f317217, v59
	v_fma_f32 v61, v59, s44, -v61
	v_fmac_f32_e32 v61, 0x3377d1cf, v59
	v_fmac_f32_e32 v61, 0x3f317217, v59
	v_cmp_lt_f32_e64 s[38:39], |v59|, s45
	s_nop 1
	v_cndmask_b32_e64 v59, v59, v61, s[38:39]
	v_cndmask_b32_e32 v61, 0, v161, vcc
	v_sub_f32_e32 v59, v59, v61
	v_add_f32_e32 v59, v60, v59
	ds_read_b128 v[60:63], v48 offset:19200
	ds_read_b128 v[68:71], v48 offset:19216
	ds_read_b128 v[72:75], v48 offset:19232
	ds_read_b128 v[76:79], v48 offset:19248
	s_waitcnt lgkmcnt(3)
	v_fma_f32 v64, v23, v60, v47
	v_fmac_f32_e32 v64, v24, v61
	v_fmac_f32_e32 v64, v25, v62
	v_fmac_f32_e32 v64, v26, v63
	s_waitcnt lgkmcnt(2)
	v_fmac_f32_e32 v64, v19, v68
	v_fmac_f32_e32 v64, v20, v69
	v_fmac_f32_e32 v64, v21, v70
	v_fmac_f32_e32 v64, v22, v71
	s_waitcnt lgkmcnt(1)
	v_fmac_f32_e32 v64, v0, v72
	v_fmac_f32_e32 v64, v18, v73
	v_pk_mul_f32 v[60:61], v[16:17], v[74:75]
	s_nop 0
	v_add_f32_e32 v60, v64, v60
	v_add_f32_e32 v64, v60, v61
	s_waitcnt lgkmcnt(0)
	v_pk_mul_f32 v[60:61], v[14:15], v[76:77]
	s_nop 0
	v_add_f32_e32 v60, v64, v60
	v_add_f32_e32 v64, v60, v61
	v_pk_mul_f32 v[60:61], v[12:13], v[78:79]
	s_nop 0
	v_add_f32_e32 v60, v64, v60
	v_add_f32_e32 v60, v60, v61
	v_max_f32_e64 v61, -v60, 0
	v_mul_f32_e64 v60, |v60|, s46
	v_exp_f32_e32 v60, v60
	s_nop 0
	v_add_f32_e32 v60, 1.0, v60
	v_cmp_gt_f32_e32 vcc, s84, v60
	s_nop 1
	v_cndmask_b32_e64 v62, 0, 32, vcc
	v_ldexp_f32 v60, v60, v62
	v_log_f32_e32 v60, v60
	s_nop 0
	v_mul_f32_e32 v62, 0x3f317217, v60
	v_fma_f32 v62, v60, s44, -v62
	v_fmac_f32_e32 v62, 0x3377d1cf, v60
	v_fmac_f32_e32 v62, 0x3f317217, v60
	v_cmp_lt_f32_e64 s[38:39], |v60|, s45
	s_nop 1
	v_cndmask_b32_e64 v60, v60, v62, s[38:39]
	v_cndmask_b32_e32 v62, 0, v161, vcc
	v_sub_f32_e32 v60, v60, v62
	ds_read_b128 v[62:65], v48 offset:19264
	ds_read_b128 v[68:71], v48 offset:19280
	ds_read_b128 v[72:75], v48 offset:19296
	ds_read_b128 v[76:79], v48 offset:19312
	v_add_f32_e32 v60, v61, v60
	s_waitcnt lgkmcnt(3)
	v_fma_f32 v61, v23, v62, v47
	v_fmac_f32_e32 v61, v24, v63
	v_fmac_f32_e32 v61, v25, v64
	v_fmac_f32_e32 v61, v26, v65
	s_waitcnt lgkmcnt(2)
	v_fmac_f32_e32 v61, v19, v68
	v_fmac_f32_e32 v61, v20, v69
	v_fmac_f32_e32 v61, v21, v70
	v_fmac_f32_e32 v61, v22, v71
	s_waitcnt lgkmcnt(1)
	v_fmac_f32_e32 v61, v0, v72
	v_fmac_f32_e32 v61, v18, v73
	v_pk_mul_f32 v[62:63], v[16:17], v[74:75]
	s_nop 0
	v_add_f32_e32 v61, v61, v62
	v_add_f32_e32 v61, v61, v63
	s_waitcnt lgkmcnt(0)
	v_pk_mul_f32 v[62:63], v[14:15], v[76:77]
	s_nop 0
	v_add_f32_e32 v61, v61, v62
	v_add_f32_e32 v61, v61, v63
	v_pk_mul_f32 v[62:63], v[12:13], v[78:79]
	s_nop 0
	v_add_f32_e32 v61, v61, v62
	v_add_f32_e32 v61, v61, v63
	v_max_f32_e64 v62, -v61, 0
	v_mul_f32_e64 v61, |v61|, s46
	v_exp_f32_e32 v61, v61
	s_nop 0
	v_add_f32_e32 v61, 1.0, v61
	v_cmp_gt_f32_e32 vcc, s84, v61
	s_nop 1
	v_cndmask_b32_e64 v63, 0, 32, vcc
	v_ldexp_f32 v61, v61, v63
	v_log_f32_e32 v61, v61
	s_nop 0
	v_mul_f32_e32 v63, 0x3f317217, v61
	v_fma_f32 v63, v61, s44, -v63
	v_fmac_f32_e32 v63, 0x3377d1cf, v61
	v_fmac_f32_e32 v63, 0x3f317217, v61
	v_cmp_lt_f32_e64 s[38:39], |v61|, s45
	s_nop 1
	v_cndmask_b32_e64 v61, v61, v63, s[38:39]
	v_cndmask_b32_e32 v63, 0, v161, vcc
	v_sub_f32_e32 v61, v61, v63
	v_add_f32_e32 v61, v62, v61
	ds_read_b128 v[62:65], v48 offset:19328
	ds_read_b128 v[68:71], v48 offset:19344
	ds_read_b128 v[72:75], v48 offset:19360
	ds_read_b128 v[76:79], v48 offset:19376
	s_waitcnt lgkmcnt(3)
	v_fma_f32 v66, v23, v62, v47
	v_fmac_f32_e32 v66, v24, v63
	v_fmac_f32_e32 v66, v25, v64
	v_fmac_f32_e32 v66, v26, v65
	s_waitcnt lgkmcnt(2)
	v_fmac_f32_e32 v66, v19, v68
	v_fmac_f32_e32 v66, v20, v69
	v_fmac_f32_e32 v66, v21, v70
	v_fmac_f32_e32 v66, v22, v71
	s_waitcnt lgkmcnt(1)
	v_fmac_f32_e32 v66, v0, v72
	v_fmac_f32_e32 v66, v18, v73
	v_pk_mul_f32 v[62:63], v[16:17], v[74:75]
	s_nop 0
	v_add_f32_e32 v62, v66, v62
	v_add_f32_e32 v66, v62, v63
	s_waitcnt lgkmcnt(0)
	v_pk_mul_f32 v[62:63], v[14:15], v[76:77]
	s_nop 0
	v_add_f32_e32 v62, v66, v62
	v_add_f32_e32 v66, v62, v63
	v_pk_mul_f32 v[62:63], v[12:13], v[78:79]
	s_nop 0
	v_add_f32_e32 v62, v66, v62
	v_add_f32_e32 v62, v62, v63
	v_max_f32_e64 v63, -v62, 0
	v_mul_f32_e64 v62, |v62|, s46
	v_exp_f32_e32 v62, v62
	s_nop 0
	v_add_f32_e32 v62, 1.0, v62
	v_cmp_gt_f32_e32 vcc, s84, v62
	s_nop 1
	v_cndmask_b32_e64 v64, 0, 32, vcc
	v_ldexp_f32 v62, v62, v64
	v_log_f32_e32 v62, v62
	s_nop 0
	v_mul_f32_e32 v64, 0x3f317217, v62
	v_fma_f32 v64, v62, s44, -v64
	v_fmac_f32_e32 v64, 0x3377d1cf, v62
	v_fmac_f32_e32 v64, 0x3f317217, v62
	v_cmp_lt_f32_e64 s[38:39], |v62|, s45
	s_nop 1
	v_cndmask_b32_e64 v62, v62, v64, s[38:39]
	v_cndmask_b32_e32 v64, 0, v161, vcc
	v_sub_f32_e32 v62, v62, v64
	v_add_f32_e32 v66, v63, v62
	ds_read_b128 v[62:65], v48 offset:19392
	s_waitcnt lgkmcnt(0)
	v_fmac_f32_e32 v47, v23, v62
	v_fmac_f32_e32 v47, v24, v63
	v_fmac_f32_e32 v47, v25, v64
	v_fmac_f32_e32 v47, v26, v65
	ds_read_b128 v[62:65], v48 offset:19408
	s_waitcnt lgkmcnt(0)
	v_fmac_f32_e32 v47, v19, v62
	v_fmac_f32_e32 v47, v20, v63
	v_fmac_f32_e32 v47, v21, v64
	v_fmac_f32_e32 v47, v22, v65
	ds_read_b128 v[20:23], v48 offset:19424
	s_waitcnt lgkmcnt(0)
	v_fmac_f32_e32 v47, v0, v20
	v_fmac_f32_e32 v47, v18, v21
	v_pk_mul_f32 v[16:17], v[16:17], v[22:23]
	s_nop 0
	v_add_f32_e32 v0, v47, v16
	v_add_f32_e32 v0, v0, v17
	ds_read_b128 v[16:19], v48 offset:19440
	v_lshl_or_b32 v47, s6, 2, v11
	s_mov_b32 s6, 0xbd800000
	v_fma_f32 v26, v27, s6, 0
	v_fmamk_f32 v27, v49, 0xbd800000, v26
	s_waitcnt lgkmcnt(0)
	v_pk_mul_f32 v[14:15], v[14:15], v[16:17]
	v_pk_mul_f32 v[12:13], v[12:13], v[18:19]
	v_add_f32_e32 v0, v0, v14
	v_add_f32_e32 v0, v0, v15
	v_add_f32_e32 v0, v0, v12
	v_add_f32_e32 v0, v0, v13
	v_max_f32_e64 v12, -v0, 0
	v_mul_f32_e64 v0, |v0|, s46
	v_exp_f32_e32 v0, v0
	v_fmamk_f32 v24, v50, 0xbd800000, v27
	v_fmamk_f32 v25, v51, 0xbd800000, v24
	v_fmamk_f32 v22, v52, 0xbd800000, v25
	v_add_f32_e32 v0, 1.0, v0
	v_cmp_gt_f32_e32 vcc, s84, v0
	v_fmamk_f32 v23, v53, 0xbd800000, v22
	v_fmamk_f32 v20, v54, 0xbd800000, v23
	v_cndmask_b32_e64 v13, 0, 32, vcc
	v_ldexp_f32 v0, v0, v13
	v_log_f32_e32 v0, v0
	v_fmamk_f32 v21, v55, 0xbd800000, v20
	v_fmamk_f32 v18, v56, 0xbd800000, v21
	v_fmamk_f32 v19, v57, 0xbd800000, v18
	v_mul_f32_e32 v13, 0x3f317217, v0
	v_fma_f32 v13, v0, s44, -v13
	v_fmac_f32_e32 v13, 0x3377d1cf, v0
	v_fmamk_f32 v16, v58, 0xbd800000, v19
	v_fmac_f32_e32 v13, 0x3f317217, v0
	v_cmp_lt_f32_e64 s[38:39], |v0|, s45
	v_fmamk_f32 v17, v59, 0xbd800000, v16
	v_fmamk_f32 v14, v60, 0xbd800000, v17
	v_cndmask_b32_e64 v0, v0, v13, s[38:39]
	v_cndmask_b32_e32 v13, 0, v161, vcc
	v_sub_f32_e32 v0, v0, v13
	v_fmamk_f32 v15, v61, 0xbd800000, v14
	v_add_f32_e32 v0, v12, v0
	v_fmamk_f32 v12, v66, 0xbd800000, v15
	v_fmamk_f32 v13, v0, 0xbd800000, v12
	ds_write_b32 v47, v13 offset:22528
	s_waitcnt lgkmcnt(0)
	s_barrier
	ds_read2st64_b32 v[48:49], v11 offset0:88 offset1:89
	ds_read2st64_b32 v[50:51], v11 offset0:90 offset1:91
	s_cselect_b64 vcc, -1, 0
	s_cmp_gt_i32 s35, 1
	s_cselect_b64 s[38:39], -1, 0
	s_waitcnt lgkmcnt(1)
	v_add_f32_e32 v47, 0, v48
	v_cndmask_b32_e32 v0, 0, v47, vcc
	v_add_f32_e32 v48, v49, v0
	s_cmp_gt_i32 s35, 2
	v_cndmask_b32_e64 v0, v0, v48, s[38:39]
	s_cselect_b64 s[40:41], -1, 0
	s_waitcnt lgkmcnt(0)
	v_add_f32_e32 v11, v50, v0
	s_cmp_gt_i32 s35, 3
	v_cndmask_b32_e64 v0, v0, v11, s[40:41]
	s_cselect_b64 s[42:43], -1, 0
	v_add_f32_e32 v11, v51, v0
	v_cndmask_b32_e64 v0, v0, v11, s[42:43]
	v_pk_add_f32 v[12:13], v[12:13], v[0:1] op_sel_hi:[1,0]
	v_pk_add_f32 v[14:15], v[14:15], v[0:1] op_sel_hi:[1,0]
	v_pk_add_f32 v[16:17], v[16:17], v[0:1] op_sel_hi:[1,0]
	v_pk_add_f32 v[18:19], v[18:19], v[0:1] op_sel_hi:[1,0]
	v_pk_add_f32 v[20:21], v[20:21], v[0:1] op_sel_hi:[1,0]
	v_pk_add_f32 v[22:23], v[22:23], v[0:1] op_sel_hi:[1,0]
	v_pk_add_f32 v[24:25], v[24:25], v[0:1] op_sel_hi:[1,0]
	v_pk_add_f32 v[26:27], v[26:27], v[0:1] op_sel_hi:[1,0]
	v_add_f32_e32 v0, v47, v49
	v_add_f32_e32 v0, v0, v50
	v_add_f32_e32 v11, v0, v51
